# ping-pong K-loops: s_setprio 1 hoisted above the segment barrier and the dead post-barrier lgkmcnt(0) dropped (two issue slots less per hand-off)
# speedup vs baseline: 1.0041x; 1.0041x over previous
.LBB0_288:
	s_ashr_i32 s53, s52, 31
	s_lshl_b64 s[54:55], s[52:53], 19
	s_add_u32 s54, s66, s54
	s_addc_u32 s55, s67, s55
	s_and_b64 s[56:57], s[40:41], exec
	s_cselect_b32 s53, s55, s61
	s_cselect_b32 s80, s54, s60
	s_ashr_i32 s43, s42, 31
	s_lshl_b64 s[56:57], s[42:43], 19
	s_add_u32 s56, s68, s56
	s_addc_u32 s57, s69, s57
	s_and_b64 s[62:63], s[40:41], exec
	s_cselect_b32 s43, s57, s59
	s_cselect_b32 s81, s56, s58
	s_add_u32 s82, s58, 0x100
	s_addc_u32 s83, s59, 0
	s_add_u32 s58, s60, 0x40080
	s_addc_u32 s59, s61, 0
	s_mov_b32 s84, -2
	s_add_u32 s60, s58, 0xfffc0080
	s_addc_u32 s61, s59, -1
	s_add_i32 s85, 0, 0x10000
	s_cmp_eq_u32 s84, 12
	s_cselect_b32 s63, s53, s61
	s_cselect_b32 s62, s80, s60
	v_add_u32_e32 v140, s85, v142
	s_cselect_b32 s61, s43, s83
	s_cselect_b32 s60, s81, s82
	s_add_i32 s90, 0, 0x14000
	ds_read_b128 v[156:159], v140
	ds_read_b128 v[160:163], v140 offset:1024
	ds_read_b128 v[164:167], v140 offset:2048
	ds_read_b128 v[168:171], v140 offset:3072
	v_add_u32_e32 v140, s90, v142
	ds_read_b128 v[172:175], v140
	ds_read_b128 v[176:179], v140 offset:1024
	ds_read_b128 v[180:183], v140 offset:2048
	ds_read_b128 v[184:187], v140 offset:3072
	v_lshl_add_u64 v[140:141], s[58:59], 0, v[138:139]
	s_add_i32 m0, s71, 0xc000
	ds_read_b128 v[188:191], v144
	ds_read_b128 v[192:195], v144 offset:1024
	ds_read_b128 v[196:199], v144 offset:2048
	ds_read_b128 v[200:203], v144 offset:3072
	ds_read_b128 v[204:207], v144 offset:4096
	ds_read_b128 v[218:221], v144 offset:5120
	ds_read_b128 v[222:225], v144 offset:6144
	ds_read_b128 v[226:229], v144 offset:7168
	global_load_lds_dwordx4 v[140:141], off
	v_lshl_add_u64 v[140:141], s[58:59], 0, v[136:137]
	s_add_i32 m0, s71, 0xe000
	s_nop 0
	global_load_lds_dwordx4 v[140:141], off
	s_waitcnt vmcnt(8)
	s_waitcnt lgkmcnt(0)
	s_setprio 1
	s_barrier
	v_mfma_f32_16x16x32_bf16 v[124:127], v[156:159], v[188:191], 0
	v_mfma_f32_16x16x32_bf16 v[120:123], v[164:167], v[188:191], 0
	v_mfma_f32_16x16x32_bf16 v[112:115], v[156:159], v[196:199], 0
	v_mfma_f32_16x16x32_bf16 v[104:107], v[164:167], v[196:199], 0
	v_mfma_f32_16x16x32_bf16 v[96:99], v[156:159], v[204:207], 0
	v_mfma_f32_16x16x32_bf16 v[88:91], v[164:167], v[204:207], 0
	v_mfma_f32_16x16x32_bf16 v[80:83], v[156:159], v[222:225], 0
	v_mfma_f32_16x16x32_bf16 v[72:75], v[164:167], v[222:225], 0
	v_mfma_f32_16x16x32_bf16 v[124:127], v[160:163], v[192:195], v[124:127]
	v_mfma_f32_16x16x32_bf16 v[120:123], v[168:171], v[192:195], v[120:123]
	v_mfma_f32_16x16x32_bf16 v[112:115], v[160:163], v[200:203], v[112:115]
	v_mfma_f32_16x16x32_bf16 v[104:107], v[168:171], v[200:203], v[104:107]
	v_mfma_f32_16x16x32_bf16 v[96:99], v[160:163], v[218:221], v[96:99]
	v_mfma_f32_16x16x32_bf16 v[88:91], v[168:171], v[218:221], v[88:91]
	v_mfma_f32_16x16x32_bf16 v[80:83], v[160:163], v[226:229], v[80:83]
	v_mfma_f32_16x16x32_bf16 v[72:75], v[168:171], v[226:229], v[72:75]
	s_setprio 0
	s_setprio 1
	v_mfma_f32_16x16x32_bf16 v[116:119], v[172:175], v[188:191], 0
	v_mfma_f32_16x16x32_bf16 v[108:111], v[180:183], v[188:191], 0
	v_mfma_f32_16x16x32_bf16 v[100:103], v[172:175], v[196:199], 0
	v_mfma_f32_16x16x32_bf16 v[92:95], v[180:183], v[196:199], 0
	v_mfma_f32_16x16x32_bf16 v[84:87], v[172:175], v[204:207], 0
	v_mfma_f32_16x16x32_bf16 v[76:79], v[180:183], v[204:207], 0
	v_mfma_f32_16x16x32_bf16 v[68:71], v[172:175], v[222:225], 0
	v_mfma_f32_16x16x32_bf16 v[64:67], v[180:183], v[222:225], 0
	v_mfma_f32_16x16x32_bf16 v[116:119], v[176:179], v[192:195], v[116:119]
	v_mfma_f32_16x16x32_bf16 v[108:111], v[184:187], v[192:195], v[108:111]
	v_mfma_f32_16x16x32_bf16 v[100:103], v[176:179], v[200:203], v[100:103]
	v_mfma_f32_16x16x32_bf16 v[92:95], v[184:187], v[200:203], v[92:95]
	v_mfma_f32_16x16x32_bf16 v[84:87], v[176:179], v[218:221], v[84:87]
	v_mfma_f32_16x16x32_bf16 v[76:79], v[184:187], v[218:221], v[76:79]
	v_mfma_f32_16x16x32_bf16 v[68:71], v[176:179], v[226:229], v[68:71]
	v_mfma_f32_16x16x32_bf16 v[64:67], v[184:187], v[226:229], v[64:67]
	s_setprio 0
	s_barrier
	s_add_i32 s85, s85, s70
	v_lshl_add_u64 v[140:141], s[60:61], 0, v[148:149]
	s_mov_b32 m0, s85
	ds_read_b128 v[188:191], v144 offset:16384
	ds_read_b128 v[192:195], v144 offset:17408
	ds_read_b128 v[196:199], v144 offset:18432
	ds_read_b128 v[200:203], v144 offset:19456
	ds_read_b128 v[204:207], v144 offset:20480
	ds_read_b128 v[218:221], v144 offset:21504
	ds_read_b128 v[222:225], v144 offset:22528
	ds_read_b128 v[226:229], v144 offset:23552
	global_load_lds_dwordx4 v[140:141], off
	s_add_i32 m0, s85, 0x2000
	s_add_u32 s88, s60, 0x40000
	v_lshl_add_u64 v[146:147], s[60:61], 0, v[130:131]
	s_addc_u32 s89, s61, 0
	s_add_i32 s85, s90, s70
	global_load_lds_dwordx4 v[146:147], off
	v_lshl_add_u64 v[208:209], s[88:89], 0, v[148:149]
	s_mov_b32 m0, s85
	v_lshl_add_u64 v[212:213], s[62:63], 0, v[132:133]
	global_load_lds_dwordx4 v[208:209], off
	v_lshl_add_u64 v[208:209], s[88:89], 0, v[130:131]
	s_add_i32 m0, s85, 0x2000
	s_nop 0
	global_load_lds_dwordx4 v[208:209], off
	v_lshl_add_u64 v[208:209], s[62:63], 0, v[134:135]
	s_mov_b32 m0, s71
	s_nop 0
	global_load_lds_dwordx4 v[208:209], off
	s_mov_b32 m0, s72
	s_nop 0
	global_load_lds_dwordx4 v[212:213], off
	s_waitcnt vmcnt(8)
	s_waitcnt lgkmcnt(0)
	s_setprio 1
	s_barrier
	v_mfma_f32_16x16x32_bf16 v[60:63], v[156:159], v[188:191], 0
	v_mfma_f32_16x16x32_bf16 v[56:59], v[164:167], v[188:191], 0
	v_mfma_f32_16x16x32_bf16 v[48:51], v[156:159], v[196:199], 0
	v_mfma_f32_16x16x32_bf16 v[40:43], v[164:167], v[196:199], 0
	v_mfma_f32_16x16x32_bf16 v[32:35], v[156:159], v[204:207], 0
	v_mfma_f32_16x16x32_bf16 v[24:27], v[164:167], v[204:207], 0
	v_mfma_f32_16x16x32_bf16 v[16:19], v[156:159], v[222:225], 0
	v_mfma_f32_16x16x32_bf16 v[8:11], v[164:167], v[222:225], 0
	v_mfma_f32_16x16x32_bf16 v[60:63], v[160:163], v[192:195], v[60:63]
	v_mfma_f32_16x16x32_bf16 v[56:59], v[168:171], v[192:195], v[56:59]
	v_mfma_f32_16x16x32_bf16 v[48:51], v[160:163], v[200:203], v[48:51]
	v_mfma_f32_16x16x32_bf16 v[40:43], v[168:171], v[200:203], v[40:43]
	v_mfma_f32_16x16x32_bf16 v[32:35], v[160:163], v[218:221], v[32:35]
	v_mfma_f32_16x16x32_bf16 v[24:27], v[168:171], v[218:221], v[24:27]
	v_mfma_f32_16x16x32_bf16 v[16:19], v[160:163], v[226:229], v[16:19]
	v_mfma_f32_16x16x32_bf16 v[8:11], v[168:171], v[226:229], v[8:11]
	s_setprio 0
	s_setprio 1
	v_mfma_f32_16x16x32_bf16 v[52:55], v[172:175], v[188:191], 0
	v_mfma_f32_16x16x32_bf16 v[44:47], v[180:183], v[188:191], 0
	v_mfma_f32_16x16x32_bf16 v[36:39], v[172:175], v[196:199], 0
	v_mfma_f32_16x16x32_bf16 v[28:31], v[180:183], v[196:199], 0
	v_mfma_f32_16x16x32_bf16 v[20:23], v[172:175], v[204:207], 0
	v_mfma_f32_16x16x32_bf16 v[12:15], v[180:183], v[204:207], 0
	v_mfma_f32_16x16x32_bf16 v[4:7], v[172:175], v[222:225], 0
	v_mfma_f32_16x16x32_bf16 v[0:3], v[180:183], v[222:225], 0
	v_mfma_f32_16x16x32_bf16 v[52:55], v[176:179], v[192:195], v[52:55]
	v_mfma_f32_16x16x32_bf16 v[44:47], v[184:187], v[192:195], v[44:47]
	v_mfma_f32_16x16x32_bf16 v[36:39], v[176:179], v[200:203], v[36:39]
	v_mfma_f32_16x16x32_bf16 v[28:31], v[184:187], v[200:203], v[28:31]
	v_mfma_f32_16x16x32_bf16 v[20:23], v[176:179], v[218:221], v[20:23]
	v_mfma_f32_16x16x32_bf16 v[12:15], v[184:187], v[218:221], v[12:15]
	v_mfma_f32_16x16x32_bf16 v[4:7], v[176:179], v[226:229], v[4:7]
	v_mfma_f32_16x16x32_bf16 v[0:3], v[184:187], v[226:229], v[0:3]
	s_setprio 0
	s_barrier
	s_branch .Lg1_p3
	.p2align 6
	.fill 12, 4, 0xBF800000
.LBB0_289:
	s_add_u32 s60, s58, 0xfffc0080
	s_addc_u32 s61, s59, -1
	s_add_i32 s85, 0, 0x10000
	s_cmp_eq_u32 s84, 12
	s_cselect_b32 s63, s53, s61
	s_cselect_b32 s62, s80, s60
	v_add_u32_e32 v140, s85, v142
	s_cselect_b32 s61, s43, s83
	s_cselect_b32 s60, s81, s82
	s_add_i32 s90, 0, 0x14000
	ds_read_b128 v[156:159], v140
	ds_read_b128 v[160:163], v140 offset:1024
	ds_read_b128 v[164:167], v140 offset:2048
	ds_read_b128 v[168:171], v140 offset:3072
	v_add_u32_e32 v140, s90, v142
	ds_read_b128 v[172:175], v140
	ds_read_b128 v[176:179], v140 offset:1024
	ds_read_b128 v[180:183], v140 offset:2048
	ds_read_b128 v[184:187], v140 offset:3072
	v_lshl_add_u64 v[140:141], s[58:59], 0, v[138:139]
	s_add_i32 m0, s71, 0xc000
	ds_read_b128 v[188:191], v144
	ds_read_b128 v[192:195], v144 offset:1024
	ds_read_b128 v[196:199], v144 offset:2048
	ds_read_b128 v[200:203], v144 offset:3072
	ds_read_b128 v[204:207], v144 offset:4096
	ds_read_b128 v[218:221], v144 offset:5120
	ds_read_b128 v[222:225], v144 offset:6144
	ds_read_b128 v[226:229], v144 offset:7168
	global_load_lds_dwordx4 v[140:141], off
	v_lshl_add_u64 v[140:141], s[58:59], 0, v[136:137]
	s_add_i32 m0, s71, 0xe000
	s_nop 0
	global_load_lds_dwordx4 v[140:141], off
	s_waitcnt vmcnt(8)
	s_waitcnt lgkmcnt(0)
	s_setprio 1
	s_barrier
	v_mfma_f32_16x16x32_bf16 v[124:127], v[156:159], v[188:191], v[124:127]
	v_mfma_f32_16x16x32_bf16 v[120:123], v[164:167], v[188:191], v[120:123]
	v_mfma_f32_16x16x32_bf16 v[112:115], v[156:159], v[196:199], v[112:115]
	v_mfma_f32_16x16x32_bf16 v[104:107], v[164:167], v[196:199], v[104:107]
	v_mfma_f32_16x16x32_bf16 v[96:99], v[156:159], v[204:207], v[96:99]
	v_mfma_f32_16x16x32_bf16 v[88:91], v[164:167], v[204:207], v[88:91]
	v_mfma_f32_16x16x32_bf16 v[80:83], v[156:159], v[222:225], v[80:83]
	v_mfma_f32_16x16x32_bf16 v[72:75], v[164:167], v[222:225], v[72:75]
	v_mfma_f32_16x16x32_bf16 v[124:127], v[160:163], v[192:195], v[124:127]
	v_mfma_f32_16x16x32_bf16 v[120:123], v[168:171], v[192:195], v[120:123]
	v_mfma_f32_16x16x32_bf16 v[112:115], v[160:163], v[200:203], v[112:115]
	v_mfma_f32_16x16x32_bf16 v[104:107], v[168:171], v[200:203], v[104:107]
	v_mfma_f32_16x16x32_bf16 v[96:99], v[160:163], v[218:221], v[96:99]
	v_mfma_f32_16x16x32_bf16 v[88:91], v[168:171], v[218:221], v[88:91]
	v_mfma_f32_16x16x32_bf16 v[80:83], v[160:163], v[226:229], v[80:83]
	v_mfma_f32_16x16x32_bf16 v[72:75], v[168:171], v[226:229], v[72:75]
	s_setprio 0
	s_setprio 1
	v_mfma_f32_16x16x32_bf16 v[116:119], v[172:175], v[188:191], v[116:119]
	v_mfma_f32_16x16x32_bf16 v[108:111], v[180:183], v[188:191], v[108:111]
	v_mfma_f32_16x16x32_bf16 v[100:103], v[172:175], v[196:199], v[100:103]
	v_mfma_f32_16x16x32_bf16 v[92:95], v[180:183], v[196:199], v[92:95]
	v_mfma_f32_16x16x32_bf16 v[84:87], v[172:175], v[204:207], v[84:87]
	v_mfma_f32_16x16x32_bf16 v[76:79], v[180:183], v[204:207], v[76:79]
	v_mfma_f32_16x16x32_bf16 v[68:71], v[172:175], v[222:225], v[68:71]
	v_mfma_f32_16x16x32_bf16 v[64:67], v[180:183], v[222:225], v[64:67]
	v_mfma_f32_16x16x32_bf16 v[116:119], v[176:179], v[192:195], v[116:119]
	v_mfma_f32_16x16x32_bf16 v[108:111], v[184:187], v[192:195], v[108:111]
	v_mfma_f32_16x16x32_bf16 v[100:103], v[176:179], v[200:203], v[100:103]
	v_mfma_f32_16x16x32_bf16 v[92:95], v[184:187], v[200:203], v[92:95]
	v_mfma_f32_16x16x32_bf16 v[84:87], v[176:179], v[218:221], v[84:87]
	v_mfma_f32_16x16x32_bf16 v[76:79], v[184:187], v[218:221], v[76:79]
	v_mfma_f32_16x16x32_bf16 v[68:71], v[176:179], v[226:229], v[68:71]
	v_mfma_f32_16x16x32_bf16 v[64:67], v[184:187], v[226:229], v[64:67]
	s_setprio 0
	s_barrier
	s_add_i32 s85, s85, s70
	v_lshl_add_u64 v[140:141], s[60:61], 0, v[148:149]
	s_mov_b32 m0, s85
	ds_read_b128 v[188:191], v144 offset:16384
	ds_read_b128 v[192:195], v144 offset:17408
	ds_read_b128 v[196:199], v144 offset:18432
	ds_read_b128 v[200:203], v144 offset:19456
	ds_read_b128 v[204:207], v144 offset:20480
	ds_read_b128 v[218:221], v144 offset:21504
	ds_read_b128 v[222:225], v144 offset:22528
	ds_read_b128 v[226:229], v144 offset:23552
	global_load_lds_dwordx4 v[140:141], off
	s_add_i32 m0, s85, 0x2000
	s_add_u32 s88, s60, 0x40000
	v_lshl_add_u64 v[146:147], s[60:61], 0, v[130:131]
	s_addc_u32 s89, s61, 0
	s_add_i32 s85, s90, s70
	global_load_lds_dwordx4 v[146:147], off
	v_lshl_add_u64 v[208:209], s[88:89], 0, v[148:149]
	s_mov_b32 m0, s85
	v_lshl_add_u64 v[212:213], s[62:63], 0, v[132:133]
	global_load_lds_dwordx4 v[208:209], off
	v_lshl_add_u64 v[208:209], s[88:89], 0, v[130:131]
	s_add_i32 m0, s85, 0x2000
	s_nop 0
	global_load_lds_dwordx4 v[208:209], off
	v_lshl_add_u64 v[208:209], s[62:63], 0, v[134:135]
	s_mov_b32 m0, s71
	s_nop 0
	global_load_lds_dwordx4 v[208:209], off
	s_mov_b32 m0, s72
	s_nop 0
	global_load_lds_dwordx4 v[212:213], off
	s_waitcnt vmcnt(8)
	s_waitcnt lgkmcnt(0)
	s_setprio 1
	s_barrier
	v_mfma_f32_16x16x32_bf16 v[60:63], v[156:159], v[188:191], v[60:63]
	v_mfma_f32_16x16x32_bf16 v[56:59], v[164:167], v[188:191], v[56:59]
	v_mfma_f32_16x16x32_bf16 v[48:51], v[156:159], v[196:199], v[48:51]
	v_mfma_f32_16x16x32_bf16 v[40:43], v[164:167], v[196:199], v[40:43]
	v_mfma_f32_16x16x32_bf16 v[32:35], v[156:159], v[204:207], v[32:35]
	v_mfma_f32_16x16x32_bf16 v[24:27], v[164:167], v[204:207], v[24:27]
	v_mfma_f32_16x16x32_bf16 v[16:19], v[156:159], v[222:225], v[16:19]
	v_mfma_f32_16x16x32_bf16 v[8:11], v[164:167], v[222:225], v[8:11]
	v_mfma_f32_16x16x32_bf16 v[60:63], v[160:163], v[192:195], v[60:63]
	v_mfma_f32_16x16x32_bf16 v[56:59], v[168:171], v[192:195], v[56:59]
	v_mfma_f32_16x16x32_bf16 v[48:51], v[160:163], v[200:203], v[48:51]
	v_mfma_f32_16x16x32_bf16 v[40:43], v[168:171], v[200:203], v[40:43]
	v_mfma_f32_16x16x32_bf16 v[32:35], v[160:163], v[218:221], v[32:35]
	v_mfma_f32_16x16x32_bf16 v[24:27], v[168:171], v[218:221], v[24:27]
	v_mfma_f32_16x16x32_bf16 v[16:19], v[160:163], v[226:229], v[16:19]
	v_mfma_f32_16x16x32_bf16 v[8:11], v[168:171], v[226:229], v[8:11]
	s_setprio 0
	s_setprio 1
	v_mfma_f32_16x16x32_bf16 v[52:55], v[172:175], v[188:191], v[52:55]
	v_mfma_f32_16x16x32_bf16 v[44:47], v[180:183], v[188:191], v[44:47]
	v_mfma_f32_16x16x32_bf16 v[36:39], v[172:175], v[196:199], v[36:39]
	v_mfma_f32_16x16x32_bf16 v[28:31], v[180:183], v[196:199], v[28:31]
	v_mfma_f32_16x16x32_bf16 v[20:23], v[172:175], v[204:207], v[20:23]
	v_mfma_f32_16x16x32_bf16 v[12:15], v[180:183], v[204:207], v[12:15]
	v_mfma_f32_16x16x32_bf16 v[4:7], v[172:175], v[222:225], v[4:7]
	v_mfma_f32_16x16x32_bf16 v[0:3], v[180:183], v[222:225], v[0:3]
	v_mfma_f32_16x16x32_bf16 v[52:55], v[176:179], v[192:195], v[52:55]
	v_mfma_f32_16x16x32_bf16 v[44:47], v[184:187], v[192:195], v[44:47]
	v_mfma_f32_16x16x32_bf16 v[36:39], v[176:179], v[200:203], v[36:39]
	v_mfma_f32_16x16x32_bf16 v[28:31], v[184:187], v[200:203], v[28:31]
	v_mfma_f32_16x16x32_bf16 v[20:23], v[176:179], v[218:221], v[20:23]
	v_mfma_f32_16x16x32_bf16 v[12:15], v[184:187], v[218:221], v[12:15]
	v_mfma_f32_16x16x32_bf16 v[4:7], v[176:179], v[226:229], v[4:7]
	v_mfma_f32_16x16x32_bf16 v[0:3], v[184:187], v[226:229], v[0:3]
	s_setprio 0
	s_barrier
.Lg1_p3:
	s_add_i32 s85, 0, 0x18000
	v_add_u32_e32 v145, s85, v142
	s_add_i32 s88, 0, 0x1c000
	ds_read_b128 v[156:159], v145
	ds_read_b128 v[160:163], v145 offset:1024
	ds_read_b128 v[164:167], v145 offset:2048
	ds_read_b128 v[168:171], v145 offset:3072
	v_add_u32_e32 v145, s88, v142
	ds_read_b128 v[172:175], v145
	ds_read_b128 v[176:179], v145 offset:1024
	ds_read_b128 v[180:183], v145 offset:2048
	ds_read_b128 v[184:187], v145 offset:3072
	s_add_u32 s62, s62, 0x40000
	s_addc_u32 s63, s63, 0
	s_mov_b32 m0, s73
	v_lshl_add_u64 v[230:231], s[62:63], 0, v[134:135]
	ds_read_b128 v[188:191], v144 offset:32768
	ds_read_b128 v[192:195], v144 offset:33792
	ds_read_b128 v[196:199], v144 offset:34816
	ds_read_b128 v[200:203], v144 offset:35840
	ds_read_b128 v[204:207], v144 offset:36864
	ds_read_b128 v[218:221], v144 offset:37888
	ds_read_b128 v[222:225], v144 offset:38912
	ds_read_b128 v[226:229], v144 offset:39936
	global_load_lds_dwordx4 v[230:231], off
	v_lshl_add_u64 v[230:231], s[62:63], 0, v[132:133]
	s_mov_b32 m0, s74
	s_nop 0
	global_load_lds_dwordx4 v[230:231], off
	s_waitcnt vmcnt(8)
	s_waitcnt lgkmcnt(0)
	s_setprio 1
	s_barrier
	v_mfma_f32_16x16x32_bf16 v[124:127], v[156:159], v[188:191], v[124:127]
	v_mfma_f32_16x16x32_bf16 v[120:123], v[164:167], v[188:191], v[120:123]
	v_mfma_f32_16x16x32_bf16 v[112:115], v[156:159], v[196:199], v[112:115]
	v_mfma_f32_16x16x32_bf16 v[104:107], v[164:167], v[196:199], v[104:107]
	v_mfma_f32_16x16x32_bf16 v[96:99], v[156:159], v[204:207], v[96:99]
	v_mfma_f32_16x16x32_bf16 v[88:91], v[164:167], v[204:207], v[88:91]
	v_mfma_f32_16x16x32_bf16 v[80:83], v[156:159], v[222:225], v[80:83]
	v_mfma_f32_16x16x32_bf16 v[72:75], v[164:167], v[222:225], v[72:75]
	v_mfma_f32_16x16x32_bf16 v[124:127], v[160:163], v[192:195], v[124:127]
	v_mfma_f32_16x16x32_bf16 v[120:123], v[168:171], v[192:195], v[120:123]
	v_mfma_f32_16x16x32_bf16 v[112:115], v[160:163], v[200:203], v[112:115]
	v_mfma_f32_16x16x32_bf16 v[104:107], v[168:171], v[200:203], v[104:107]
	v_mfma_f32_16x16x32_bf16 v[96:99], v[160:163], v[218:221], v[96:99]
	v_mfma_f32_16x16x32_bf16 v[88:91], v[168:171], v[218:221], v[88:91]
	v_mfma_f32_16x16x32_bf16 v[80:83], v[160:163], v[226:229], v[80:83]
	v_mfma_f32_16x16x32_bf16 v[72:75], v[168:171], v[226:229], v[72:75]
	s_setprio 0
	s_setprio 1
	v_mfma_f32_16x16x32_bf16 v[116:119], v[172:175], v[188:191], v[116:119]
	v_mfma_f32_16x16x32_bf16 v[108:111], v[180:183], v[188:191], v[108:111]
	v_mfma_f32_16x16x32_bf16 v[100:103], v[172:175], v[196:199], v[100:103]
	v_mfma_f32_16x16x32_bf16 v[92:95], v[180:183], v[196:199], v[92:95]
	v_mfma_f32_16x16x32_bf16 v[84:87], v[172:175], v[204:207], v[84:87]
	v_mfma_f32_16x16x32_bf16 v[76:79], v[180:183], v[204:207], v[76:79]
	v_mfma_f32_16x16x32_bf16 v[68:71], v[172:175], v[222:225], v[68:71]
	v_mfma_f32_16x16x32_bf16 v[64:67], v[180:183], v[222:225], v[64:67]
	v_mfma_f32_16x16x32_bf16 v[116:119], v[176:179], v[192:195], v[116:119]
	v_mfma_f32_16x16x32_bf16 v[108:111], v[184:187], v[192:195], v[108:111]
	v_mfma_f32_16x16x32_bf16 v[100:103], v[176:179], v[200:203], v[100:103]
	v_mfma_f32_16x16x32_bf16 v[92:95], v[184:187], v[200:203], v[92:95]
	v_mfma_f32_16x16x32_bf16 v[84:87], v[176:179], v[218:221], v[84:87]
	v_mfma_f32_16x16x32_bf16 v[76:79], v[184:187], v[218:221], v[76:79]
	v_mfma_f32_16x16x32_bf16 v[68:71], v[176:179], v[226:229], v[68:71]
	v_mfma_f32_16x16x32_bf16 v[64:67], v[184:187], v[226:229], v[64:67]
	s_setprio 0
	s_barrier
	s_add_i32 s62, s85, s70
	v_lshl_add_u64 v[140:141], v[140:141], 0, s[0:1]
	s_mov_b32 m0, s62
	ds_read_b128 v[188:191], v144 offset:49152
	ds_read_b128 v[192:195], v144 offset:50176
	ds_read_b128 v[196:199], v144 offset:51200
	ds_read_b128 v[200:203], v144 offset:52224
	ds_read_b128 v[204:207], v144 offset:53248
	ds_read_b128 v[218:221], v144 offset:54272
	ds_read_b128 v[222:225], v144 offset:55296
	ds_read_b128 v[226:229], v144 offset:56320
	global_load_lds_dwordx4 v[140:141], off
	s_add_i32 m0, s62, 0x2000
	s_add_u32 s60, s60, 0x40080
	v_lshl_add_u64 v[140:141], v[146:147], 0, s[0:1]
	s_addc_u32 s61, s61, 0
	s_add_i32 s62, s88, s70
	global_load_lds_dwordx4 v[140:141], off
	v_lshl_add_u64 v[140:141], s[60:61], 0, v[148:149]
	s_mov_b32 m0, s62
	s_nop 0
	global_load_lds_dwordx4 v[140:141], off
	v_lshl_add_u64 v[140:141], s[60:61], 0, v[130:131]
	s_add_i32 m0, s62, 0x2000
	s_nop 0
	global_load_lds_dwordx4 v[140:141], off
	v_lshl_add_u64 v[140:141], v[208:209], 0, s[0:1]
	s_mov_b32 m0, s75
	s_nop 0
	global_load_lds_dwordx4 v[140:141], off
	v_lshl_add_u64 v[140:141], v[212:213], 0, s[0:1]
	s_mov_b32 m0, s76
	s_nop 0
	global_load_lds_dwordx4 v[140:141], off
	s_waitcnt vmcnt(8)
	s_waitcnt lgkmcnt(0)
	s_setprio 1
	s_barrier
	v_mfma_f32_16x16x32_bf16 v[60:63], v[156:159], v[188:191], v[60:63]
	v_mfma_f32_16x16x32_bf16 v[56:59], v[164:167], v[188:191], v[56:59]
	v_mfma_f32_16x16x32_bf16 v[48:51], v[156:159], v[196:199], v[48:51]
	v_mfma_f32_16x16x32_bf16 v[40:43], v[164:167], v[196:199], v[40:43]
	v_mfma_f32_16x16x32_bf16 v[32:35], v[156:159], v[204:207], v[32:35]
	v_mfma_f32_16x16x32_bf16 v[24:27], v[164:167], v[204:207], v[24:27]
	v_mfma_f32_16x16x32_bf16 v[16:19], v[156:159], v[222:225], v[16:19]
	v_mfma_f32_16x16x32_bf16 v[8:11], v[164:167], v[222:225], v[8:11]
	v_mfma_f32_16x16x32_bf16 v[60:63], v[160:163], v[192:195], v[60:63]
	v_mfma_f32_16x16x32_bf16 v[56:59], v[168:171], v[192:195], v[56:59]
	v_mfma_f32_16x16x32_bf16 v[48:51], v[160:163], v[200:203], v[48:51]
	v_mfma_f32_16x16x32_bf16 v[40:43], v[168:171], v[200:203], v[40:43]
	v_mfma_f32_16x16x32_bf16 v[32:35], v[160:163], v[218:221], v[32:35]
	v_mfma_f32_16x16x32_bf16 v[24:27], v[168:171], v[218:221], v[24:27]
	v_mfma_f32_16x16x32_bf16 v[16:19], v[160:163], v[226:229], v[16:19]
	v_mfma_f32_16x16x32_bf16 v[8:11], v[168:171], v[226:229], v[8:11]
	s_setprio 0
	s_setprio 1
	v_mfma_f32_16x16x32_bf16 v[52:55], v[172:175], v[188:191], v[52:55]
	v_mfma_f32_16x16x32_bf16 v[44:47], v[180:183], v[188:191], v[44:47]
	v_mfma_f32_16x16x32_bf16 v[36:39], v[172:175], v[196:199], v[36:39]
	v_mfma_f32_16x16x32_bf16 v[28:31], v[180:183], v[196:199], v[28:31]
	v_mfma_f32_16x16x32_bf16 v[20:23], v[172:175], v[204:207], v[20:23]
	v_mfma_f32_16x16x32_bf16 v[12:15], v[180:183], v[204:207], v[12:15]
	v_mfma_f32_16x16x32_bf16 v[4:7], v[172:175], v[222:225], v[4:7]
	v_mfma_f32_16x16x32_bf16 v[0:3], v[180:183], v[222:225], v[0:3]
	v_mfma_f32_16x16x32_bf16 v[52:55], v[176:179], v[192:195], v[52:55]
	v_mfma_f32_16x16x32_bf16 v[44:47], v[184:187], v[192:195], v[44:47]
	v_mfma_f32_16x16x32_bf16 v[36:39], v[176:179], v[200:203], v[36:39]
	v_mfma_f32_16x16x32_bf16 v[28:31], v[184:187], v[200:203], v[28:31]
	v_mfma_f32_16x16x32_bf16 v[20:23], v[176:179], v[218:221], v[20:23]
	v_mfma_f32_16x16x32_bf16 v[12:15], v[184:187], v[218:221], v[12:15]
	v_mfma_f32_16x16x32_bf16 v[4:7], v[176:179], v[226:229], v[4:7]
	v_mfma_f32_16x16x32_bf16 v[0:3], v[184:187], v[226:229], v[0:3]
	s_setprio 0
	s_barrier
	s_add_i32 s84, s84, 2
	s_add_u32 s82, s82, 0x100
	s_addc_u32 s83, s83, 0
	s_add_u32 s58, s58, 0x100
	s_addc_u32 s59, s59, 0
	s_cmp_gt_u32 s84, 13
	s_cbranch_scc0 .LBB0_289
	s_andn2_b64 vcc, s[38:39], s[40:41]
	s_cbranch_vccz .LBB0_292
	s_barrier

.LBB0_738:
	s_add_u32 s38, s24, s36
	s_addc_u32 s39, s25, s37
	s_add_u32 s38, s38, 0x100
	s_addc_u32 s39, s39, 0
	s_add_u32 s71, s64, s36
	s_addc_u32 s72, s65, s37
	s_add_i32 s73, 0, 0x10000
	s_cmpk_eq_i32 s36, 0x700
	s_cselect_b32 s45, s29, s39
	s_cselect_b32 s44, s68, s38
	v_add_u32_e32 v143, s73, v141
	s_cselect_b32 s39, s27, s72
	s_cselect_b32 s38, s69, s71
	s_add_i32 s71, 0, 0x14000
	ds_read_b128 v[144:147], v143
	ds_read_b128 v[156:159], v143 offset:1024
	ds_read_b128 v[160:163], v143 offset:2048
	ds_read_b128 v[164:167], v143 offset:3072
	v_add_u32_e32 v143, s71, v141
	ds_read_b128 v[168:171], v143
	ds_read_b128 v[172:175], v143 offset:1024
	ds_read_b128 v[176:179], v143 offset:2048
	ds_read_b128 v[180:183], v143 offset:3072
	v_lshl_add_u64 v[154:155], v[138:139], 0, s[36:37]
	s_add_i32 m0, s48, 0xc000
	ds_read_b128 v[184:187], v142
	ds_read_b128 v[188:191], v142 offset:1024
	ds_read_b128 v[192:195], v142 offset:2048
	ds_read_b128 v[196:199], v142 offset:3072
	ds_read_b128 v[200:203], v142 offset:4096
	ds_read_b128 v[204:207], v142 offset:5120
	ds_read_b128 v[218:221], v142 offset:6144
	ds_read_b128 v[222:225], v142 offset:7168
	global_load_lds_dwordx4 v[154:155], off
	v_lshl_add_u64 v[154:155], v[136:137], 0, s[36:37]
	s_add_i32 m0, s48, 0xe000
	s_nop 0
	global_load_lds_dwordx4 v[154:155], off
	s_waitcnt vmcnt(8)
	s_waitcnt lgkmcnt(0)
	s_setprio 1
	s_barrier
	v_mfma_f32_16x16x32_bf16 v[124:127], v[144:147], v[184:187], v[124:127]
	v_mfma_f32_16x16x32_bf16 v[120:123], v[160:163], v[184:187], v[120:123]
	v_mfma_f32_16x16x32_bf16 v[108:111], v[144:147], v[192:195], v[108:111]
	v_mfma_f32_16x16x32_bf16 v[104:107], v[160:163], v[192:195], v[104:107]
	v_mfma_f32_16x16x32_bf16 v[92:95], v[144:147], v[200:203], v[92:95]
	v_mfma_f32_16x16x32_bf16 v[88:91], v[160:163], v[200:203], v[88:91]
	v_mfma_f32_16x16x32_bf16 v[76:79], v[144:147], v[218:221], v[76:79]
	v_mfma_f32_16x16x32_bf16 v[72:75], v[160:163], v[218:221], v[72:75]
	v_mfma_f32_16x16x32_bf16 v[124:127], v[156:159], v[188:191], v[124:127]
	v_mfma_f32_16x16x32_bf16 v[120:123], v[164:167], v[188:191], v[120:123]
	v_mfma_f32_16x16x32_bf16 v[108:111], v[156:159], v[196:199], v[108:111]
	v_mfma_f32_16x16x32_bf16 v[104:107], v[164:167], v[196:199], v[104:107]
	v_mfma_f32_16x16x32_bf16 v[92:95], v[156:159], v[204:207], v[92:95]
	v_mfma_f32_16x16x32_bf16 v[88:91], v[164:167], v[204:207], v[88:91]
	v_mfma_f32_16x16x32_bf16 v[76:79], v[156:159], v[222:225], v[76:79]
	v_mfma_f32_16x16x32_bf16 v[72:75], v[164:167], v[222:225], v[72:75]
	s_setprio 0
	s_setprio 1
	v_mfma_f32_16x16x32_bf16 v[116:119], v[168:171], v[184:187], v[116:119]
	v_mfma_f32_16x16x32_bf16 v[112:115], v[176:179], v[184:187], v[112:115]
	v_mfma_f32_16x16x32_bf16 v[100:103], v[168:171], v[192:195], v[100:103]
	v_mfma_f32_16x16x32_bf16 v[96:99], v[176:179], v[192:195], v[96:99]
	v_mfma_f32_16x16x32_bf16 v[84:87], v[168:171], v[200:203], v[84:87]
	v_mfma_f32_16x16x32_bf16 v[80:83], v[176:179], v[200:203], v[80:83]
	v_mfma_f32_16x16x32_bf16 v[68:71], v[168:171], v[218:221], v[68:71]
	v_mfma_f32_16x16x32_bf16 v[64:67], v[176:179], v[218:221], v[64:67]
	v_mfma_f32_16x16x32_bf16 v[116:119], v[172:175], v[188:191], v[116:119]
	v_mfma_f32_16x16x32_bf16 v[112:115], v[180:183], v[188:191], v[112:115]
	v_mfma_f32_16x16x32_bf16 v[100:103], v[172:175], v[196:199], v[100:103]
	v_mfma_f32_16x16x32_bf16 v[96:99], v[180:183], v[196:199], v[96:99]
	v_mfma_f32_16x16x32_bf16 v[84:87], v[172:175], v[204:207], v[84:87]
	v_mfma_f32_16x16x32_bf16 v[80:83], v[180:183], v[204:207], v[80:83]
	v_mfma_f32_16x16x32_bf16 v[68:71], v[172:175], v[222:225], v[68:71]
	v_mfma_f32_16x16x32_bf16 v[64:67], v[180:183], v[222:225], v[64:67]
	s_setprio 0
	s_barrier
	s_add_i32 s72, s73, s47
	v_lshl_add_u64 v[154:155], s[38:39], 0, v[148:149]
	s_mov_b32 m0, s72
	ds_read_b128 v[184:187], v142 offset:16384
	ds_read_b128 v[188:191], v142 offset:17408
	ds_read_b128 v[192:195], v142 offset:18432
	ds_read_b128 v[196:199], v142 offset:19456
	ds_read_b128 v[200:203], v142 offset:20480
	ds_read_b128 v[204:207], v142 offset:21504
	ds_read_b128 v[218:221], v142 offset:22528
	ds_read_b128 v[222:225], v142 offset:23552
	global_load_lds_dwordx4 v[154:155], off
	s_add_i32 m0, s72, 0x2000
	s_add_u32 s72, s38, 0x40000
	v_lshl_add_u64 v[208:209], s[38:39], 0, v[130:131]
	s_addc_u32 s73, s39, 0
	s_add_i32 s71, s71, s47
	global_load_lds_dwordx4 v[208:209], off
	v_lshl_add_u64 v[212:213], s[72:73], 0, v[148:149]
	s_mov_b32 m0, s71
	v_lshl_add_u64 v[226:227], s[44:45], 0, v[130:131]
	global_load_lds_dwordx4 v[212:213], off
	v_lshl_add_u64 v[212:213], s[72:73], 0, v[130:131]
	s_add_i32 m0, s71, 0x2000
	s_nop 0
	global_load_lds_dwordx4 v[212:213], off
	v_lshl_add_u64 v[212:213], s[44:45], 0, v[148:149]
	s_mov_b32 m0, s48
	s_nop 0
	global_load_lds_dwordx4 v[212:213], off
	s_mov_b32 m0, s49
	s_nop 0
	global_load_lds_dwordx4 v[226:227], off
	s_waitcnt vmcnt(8)
	s_waitcnt lgkmcnt(0)
	s_setprio 1
	s_barrier
	v_mfma_f32_16x16x32_bf16 v[60:63], v[144:147], v[184:187], v[60:63]
	v_mfma_f32_16x16x32_bf16 v[56:59], v[160:163], v[184:187], v[56:59]
	v_mfma_f32_16x16x32_bf16 v[44:47], v[144:147], v[192:195], v[44:47]
	v_mfma_f32_16x16x32_bf16 v[40:43], v[160:163], v[192:195], v[40:43]
	v_mfma_f32_16x16x32_bf16 v[28:31], v[144:147], v[200:203], v[28:31]
	v_mfma_f32_16x16x32_bf16 v[24:27], v[160:163], v[200:203], v[24:27]
	v_mfma_f32_16x16x32_bf16 v[12:15], v[144:147], v[218:221], v[12:15]
	v_mfma_f32_16x16x32_bf16 v[8:11], v[160:163], v[218:221], v[8:11]
	v_mfma_f32_16x16x32_bf16 v[60:63], v[156:159], v[188:191], v[60:63]
	v_mfma_f32_16x16x32_bf16 v[56:59], v[164:167], v[188:191], v[56:59]
	v_mfma_f32_16x16x32_bf16 v[44:47], v[156:159], v[196:199], v[44:47]
	v_mfma_f32_16x16x32_bf16 v[40:43], v[164:167], v[196:199], v[40:43]
	v_mfma_f32_16x16x32_bf16 v[28:31], v[156:159], v[204:207], v[28:31]
	v_mfma_f32_16x16x32_bf16 v[24:27], v[164:167], v[204:207], v[24:27]
	v_mfma_f32_16x16x32_bf16 v[12:15], v[156:159], v[222:225], v[12:15]
	v_mfma_f32_16x16x32_bf16 v[8:11], v[164:167], v[222:225], v[8:11]
	s_setprio 0
	s_setprio 1
	v_mfma_f32_16x16x32_bf16 v[52:55], v[168:171], v[184:187], v[52:55]
	v_mfma_f32_16x16x32_bf16 v[48:51], v[176:179], v[184:187], v[48:51]
	v_mfma_f32_16x16x32_bf16 v[36:39], v[168:171], v[192:195], v[36:39]
	v_mfma_f32_16x16x32_bf16 v[32:35], v[176:179], v[192:195], v[32:35]
	v_mfma_f32_16x16x32_bf16 v[20:23], v[168:171], v[200:203], v[20:23]
	v_mfma_f32_16x16x32_bf16 v[16:19], v[176:179], v[200:203], v[16:19]
	v_mfma_f32_16x16x32_bf16 v[4:7], v[168:171], v[218:221], v[4:7]
	v_mfma_f32_16x16x32_bf16 v[0:3], v[176:179], v[218:221], v[0:3]
	v_mfma_f32_16x16x32_bf16 v[52:55], v[172:175], v[188:191], v[52:55]
	v_mfma_f32_16x16x32_bf16 v[48:51], v[180:183], v[188:191], v[48:51]
	v_mfma_f32_16x16x32_bf16 v[36:39], v[172:175], v[196:199], v[36:39]
	v_mfma_f32_16x16x32_bf16 v[32:35], v[180:183], v[196:199], v[32:35]
	v_mfma_f32_16x16x32_bf16 v[20:23], v[172:175], v[204:207], v[20:23]
	v_mfma_f32_16x16x32_bf16 v[16:19], v[180:183], v[204:207], v[16:19]
	v_mfma_f32_16x16x32_bf16 v[4:7], v[172:175], v[222:225], v[4:7]
	v_mfma_f32_16x16x32_bf16 v[0:3], v[180:183], v[222:225], v[0:3]
	s_setprio 0
	s_barrier
	s_add_i32 s71, 0, 0x18000
	v_add_u32_e32 v143, s71, v141
	s_add_i32 s72, 0, 0x1c000
	ds_read_b128 v[144:147], v143
	ds_read_b128 v[156:159], v143 offset:1024
	ds_read_b128 v[160:163], v143 offset:2048
	ds_read_b128 v[164:167], v143 offset:3072
	v_add_u32_e32 v143, s72, v141
	ds_read_b128 v[168:171], v143
	ds_read_b128 v[172:175], v143 offset:1024
	ds_read_b128 v[176:179], v143 offset:2048
	ds_read_b128 v[180:183], v143 offset:3072
	s_add_u32 s44, s44, 0x40000
	s_addc_u32 s45, s45, 0
	s_mov_b32 m0, s58
	v_lshl_add_u64 v[228:229], s[44:45], 0, v[148:149]
	ds_read_b128 v[184:187], v142 offset:32768
	ds_read_b128 v[188:191], v142 offset:33792
	ds_read_b128 v[192:195], v142 offset:34816
	ds_read_b128 v[196:199], v142 offset:35840
	ds_read_b128 v[200:203], v142 offset:36864
	ds_read_b128 v[204:207], v142 offset:37888
	ds_read_b128 v[218:221], v142 offset:38912
	ds_read_b128 v[222:225], v142 offset:39936
	global_load_lds_dwordx4 v[228:229], off
	v_lshl_add_u64 v[228:229], s[44:45], 0, v[130:131]
	s_mov_b32 m0, s59
	s_nop 0
	global_load_lds_dwordx4 v[228:229], off
	s_waitcnt vmcnt(8)
	s_waitcnt lgkmcnt(0)
	s_setprio 1
	s_barrier
	v_mfma_f32_16x16x32_bf16 v[124:127], v[144:147], v[184:187], v[124:127]
	v_mfma_f32_16x16x32_bf16 v[120:123], v[160:163], v[184:187], v[120:123]
	v_mfma_f32_16x16x32_bf16 v[108:111], v[144:147], v[192:195], v[108:111]
	v_mfma_f32_16x16x32_bf16 v[104:107], v[160:163], v[192:195], v[104:107]
	v_mfma_f32_16x16x32_bf16 v[92:95], v[144:147], v[200:203], v[92:95]
	v_mfma_f32_16x16x32_bf16 v[88:91], v[160:163], v[200:203], v[88:91]
	v_mfma_f32_16x16x32_bf16 v[76:79], v[144:147], v[218:221], v[76:79]
	v_mfma_f32_16x16x32_bf16 v[72:75], v[160:163], v[218:221], v[72:75]
	v_mfma_f32_16x16x32_bf16 v[124:127], v[156:159], v[188:191], v[124:127]
	v_mfma_f32_16x16x32_bf16 v[120:123], v[164:167], v[188:191], v[120:123]
	v_mfma_f32_16x16x32_bf16 v[108:111], v[156:159], v[196:199], v[108:111]
	v_mfma_f32_16x16x32_bf16 v[104:107], v[164:167], v[196:199], v[104:107]
	v_mfma_f32_16x16x32_bf16 v[92:95], v[156:159], v[204:207], v[92:95]
	v_mfma_f32_16x16x32_bf16 v[88:91], v[164:167], v[204:207], v[88:91]
	v_mfma_f32_16x16x32_bf16 v[76:79], v[156:159], v[222:225], v[76:79]
	v_mfma_f32_16x16x32_bf16 v[72:75], v[164:167], v[222:225], v[72:75]
	s_setprio 0
	s_setprio 1
	v_mfma_f32_16x16x32_bf16 v[116:119], v[168:171], v[184:187], v[116:119]
	v_mfma_f32_16x16x32_bf16 v[112:115], v[176:179], v[184:187], v[112:115]
	v_mfma_f32_16x16x32_bf16 v[100:103], v[168:171], v[192:195], v[100:103]
	v_mfma_f32_16x16x32_bf16 v[96:99], v[176:179], v[192:195], v[96:99]
	v_mfma_f32_16x16x32_bf16 v[84:87], v[168:171], v[200:203], v[84:87]
	v_mfma_f32_16x16x32_bf16 v[80:83], v[176:179], v[200:203], v[80:83]
	v_mfma_f32_16x16x32_bf16 v[68:71], v[168:171], v[218:221], v[68:71]
	v_mfma_f32_16x16x32_bf16 v[64:67], v[176:179], v[218:221], v[64:67]
	v_mfma_f32_16x16x32_bf16 v[116:119], v[172:175], v[188:191], v[116:119]
	v_mfma_f32_16x16x32_bf16 v[112:115], v[180:183], v[188:191], v[112:115]
	v_mfma_f32_16x16x32_bf16 v[100:103], v[172:175], v[196:199], v[100:103]
	v_mfma_f32_16x16x32_bf16 v[96:99], v[180:183], v[196:199], v[96:99]
	v_mfma_f32_16x16x32_bf16 v[84:87], v[172:175], v[204:207], v[84:87]
	v_mfma_f32_16x16x32_bf16 v[80:83], v[180:183], v[204:207], v[80:83]
	v_mfma_f32_16x16x32_bf16 v[68:71], v[172:175], v[222:225], v[68:71]
	v_mfma_f32_16x16x32_bf16 v[64:67], v[180:183], v[222:225], v[64:67]
	s_setprio 0
	s_barrier
	s_add_i32 s44, s71, s47
	v_lshl_add_u64 v[154:155], v[154:155], 0, s[0:1]
	s_mov_b32 m0, s44
	ds_read_b128 v[184:187], v142 offset:49152
	ds_read_b128 v[188:191], v142 offset:50176
	ds_read_b128 v[192:195], v142 offset:51200
	ds_read_b128 v[196:199], v142 offset:52224
	ds_read_b128 v[200:203], v142 offset:53248
	ds_read_b128 v[204:207], v142 offset:54272
	ds_read_b128 v[218:221], v142 offset:55296
	ds_read_b128 v[222:225], v142 offset:56320
	global_load_lds_dwordx4 v[154:155], off
	s_add_i32 m0, s44, 0x2000
	s_add_u32 s38, s38, 0x40080
	v_lshl_add_u64 v[154:155], v[208:209], 0, s[0:1]
	s_addc_u32 s39, s39, 0
	s_add_i32 s44, s72, s47
	global_load_lds_dwordx4 v[154:155], off
	v_lshl_add_u64 v[154:155], s[38:39], 0, v[148:149]
	s_mov_b32 m0, s44
	s_nop 0
	global_load_lds_dwordx4 v[154:155], off
	v_lshl_add_u64 v[154:155], s[38:39], 0, v[130:131]
	s_add_i32 m0, s44, 0x2000
	s_nop 0
	global_load_lds_dwordx4 v[154:155], off
	v_lshl_add_u64 v[154:155], v[212:213], 0, s[0:1]
	s_mov_b32 m0, s60
	s_nop 0
	global_load_lds_dwordx4 v[154:155], off
	v_lshl_add_u64 v[154:155], v[226:227], 0, s[0:1]
	s_mov_b32 m0, s61
	s_nop 0
	global_load_lds_dwordx4 v[154:155], off
	s_waitcnt vmcnt(8)
	s_waitcnt lgkmcnt(0)
	s_setprio 1
	s_barrier
	v_mfma_f32_16x16x32_bf16 v[60:63], v[144:147], v[184:187], v[60:63]
	v_mfma_f32_16x16x32_bf16 v[56:59], v[160:163], v[184:187], v[56:59]
	v_mfma_f32_16x16x32_bf16 v[44:47], v[144:147], v[192:195], v[44:47]
	v_mfma_f32_16x16x32_bf16 v[40:43], v[160:163], v[192:195], v[40:43]
	v_mfma_f32_16x16x32_bf16 v[28:31], v[144:147], v[200:203], v[28:31]
	v_mfma_f32_16x16x32_bf16 v[24:27], v[160:163], v[200:203], v[24:27]
	v_mfma_f32_16x16x32_bf16 v[12:15], v[144:147], v[218:221], v[12:15]
	v_mfma_f32_16x16x32_bf16 v[8:11], v[160:163], v[218:221], v[8:11]
	v_mfma_f32_16x16x32_bf16 v[60:63], v[156:159], v[188:191], v[60:63]
	v_mfma_f32_16x16x32_bf16 v[56:59], v[164:167], v[188:191], v[56:59]
	v_mfma_f32_16x16x32_bf16 v[44:47], v[156:159], v[196:199], v[44:47]
	v_mfma_f32_16x16x32_bf16 v[40:43], v[164:167], v[196:199], v[40:43]
	v_mfma_f32_16x16x32_bf16 v[28:31], v[156:159], v[204:207], v[28:31]
	v_mfma_f32_16x16x32_bf16 v[24:27], v[164:167], v[204:207], v[24:27]
	v_mfma_f32_16x16x32_bf16 v[12:15], v[156:159], v[222:225], v[12:15]
	v_mfma_f32_16x16x32_bf16 v[8:11], v[164:167], v[222:225], v[8:11]
	s_setprio 0
	s_setprio 1
	v_mfma_f32_16x16x32_bf16 v[52:55], v[168:171], v[184:187], v[52:55]
	v_mfma_f32_16x16x32_bf16 v[48:51], v[176:179], v[184:187], v[48:51]
	v_mfma_f32_16x16x32_bf16 v[36:39], v[168:171], v[192:195], v[36:39]
	v_mfma_f32_16x16x32_bf16 v[32:35], v[176:179], v[192:195], v[32:35]
	v_mfma_f32_16x16x32_bf16 v[20:23], v[168:171], v[200:203], v[20:23]
	v_mfma_f32_16x16x32_bf16 v[16:19], v[176:179], v[200:203], v[16:19]
	v_mfma_f32_16x16x32_bf16 v[4:7], v[168:171], v[218:221], v[4:7]
	v_mfma_f32_16x16x32_bf16 v[0:3], v[176:179], v[218:221], v[0:3]
	v_mfma_f32_16x16x32_bf16 v[52:55], v[172:175], v[188:191], v[52:55]
	v_mfma_f32_16x16x32_bf16 v[48:51], v[180:183], v[188:191], v[48:51]
	v_mfma_f32_16x16x32_bf16 v[36:39], v[172:175], v[196:199], v[36:39]
	v_mfma_f32_16x16x32_bf16 v[32:35], v[180:183], v[196:199], v[32:35]
	v_mfma_f32_16x16x32_bf16 v[20:23], v[172:175], v[204:207], v[20:23]
	v_mfma_f32_16x16x32_bf16 v[16:19], v[180:183], v[204:207], v[16:19]
	v_mfma_f32_16x16x32_bf16 v[4:7], v[172:175], v[222:225], v[4:7]
	v_mfma_f32_16x16x32_bf16 v[0:3], v[180:183], v[222:225], v[0:3]
	s_setprio 0
	s_barrier
	s_add_i32 s70, s70, 2
	s_add_u32 s36, s36, 0x100
	s_addc_u32 s37, s37, 0
	s_cmp_gt_u32 s70, 13
	s_cbranch_scc0 .LBB0_738
	s_add_u32 s36, s64, 0xffffff00
	s_addc_u32 s37, s65, -1
	s_andn2_b64 vcc, exec, s[42:43]
	s_cbranch_vccnz .LBB0_741
	v_mov_b32_e32 v0, 0
	s_mov_b32 s4, s26
	s_mov_b32 s22, s28
	s_mov_b64 s[24:25], s[34:35]
	s_mov_b32 s62, s63
	v_mov_b32_e32 v1, v0
	v_mov_b32_e32 v2, v0
	v_mov_b32_e32 v3, v0
	v_mov_b32_e32 v4, v0
	v_mov_b32_e32 v5, v0
	v_mov_b32_e32 v6, v0
	v_mov_b32_e32 v7, v0
	v_mov_b32_e32 v16, v0
	v_mov_b32_e32 v17, v0
	v_mov_b32_e32 v18, v0
	v_mov_b32_e32 v19, v0
	v_mov_b32_e32 v20, v0
	v_mov_b32_e32 v21, v0
	v_mov_b32_e32 v22, v0
	v_mov_b32_e32 v23, v0
	v_mov_b32_e32 v32, v0
	v_mov_b32_e32 v33, v0
	v_mov_b32_e32 v34, v0
	v_mov_b32_e32 v35, v0
	v_mov_b32_e32 v36, v0
	v_mov_b32_e32 v37, v0
	v_mov_b32_e32 v38, v0
	v_mov_b32_e32 v39, v0
	v_mov_b32_e32 v48, v0
	v_mov_b32_e32 v49, v0
	v_mov_b32_e32 v50, v0
	v_mov_b32_e32 v51, v0
	v_mov_b32_e32 v52, v0
	v_mov_b32_e32 v53, v0
	v_mov_b32_e32 v54, v0
	v_mov_b32_e32 v55, v0
	v_mov_b32_e32 v8, v0
	v_mov_b32_e32 v9, v0
	v_mov_b32_e32 v10, v0
	v_mov_b32_e32 v11, v0
	v_mov_b32_e32 v12, v0
	v_mov_b32_e32 v13, v0
	v_mov_b32_e32 v14, v0
	v_mov_b32_e32 v15, v0
	v_mov_b32_e32 v24, v0
	v_mov_b32_e32 v25, v0
	v_mov_b32_e32 v26, v0
	v_mov_b32_e32 v27, v0
	v_mov_b32_e32 v28, v0
	v_mov_b32_e32 v29, v0
	v_mov_b32_e32 v30, v0
	v_mov_b32_e32 v31, v0
	v_mov_b32_e32 v40, v0
	v_mov_b32_e32 v41, v0
	v_mov_b32_e32 v42, v0
	v_mov_b32_e32 v43, v0
	v_mov_b32_e32 v44, v0
	v_mov_b32_e32 v45, v0
	v_mov_b32_e32 v46, v0
	v_mov_b32_e32 v47, v0
	v_mov_b32_e32 v56, v0
	v_mov_b32_e32 v57, v0
	v_mov_b32_e32 v58, v0
	v_mov_b32_e32 v59, v0
	v_mov_b32_e32 v60, v0
	v_mov_b32_e32 v61, v0
	v_mov_b32_e32 v62, v0
	v_mov_b32_e32 v63, v0
	v_mov_b32_e32 v64, v0
	v_mov_b32_e32 v65, v0
	v_mov_b32_e32 v66, v0
	v_mov_b32_e32 v67, v0
	v_mov_b32_e32 v68, v0
	v_mov_b32_e32 v69, v0
	v_mov_b32_e32 v70, v0
	v_mov_b32_e32 v71, v0
	v_mov_b32_e32 v80, v0
	v_mov_b32_e32 v81, v0
	v_mov_b32_e32 v82, v0
	v_mov_b32_e32 v83, v0
	v_mov_b32_e32 v84, v0
	v_mov_b32_e32 v85, v0
	v_mov_b32_e32 v86, v0
	v_mov_b32_e32 v87, v0
	v_mov_b32_e32 v96, v0
	v_mov_b32_e32 v97, v0
	v_mov_b32_e32 v98, v0
	v_mov_b32_e32 v99, v0
	v_mov_b32_e32 v100, v0
	v_mov_b32_e32 v101, v0
	v_mov_b32_e32 v102, v0
	v_mov_b32_e32 v103, v0
	v_mov_b32_e32 v112, v0
	v_mov_b32_e32 v113, v0
	v_mov_b32_e32 v114, v0
	v_mov_b32_e32 v115, v0
	v_mov_b32_e32 v116, v0
	v_mov_b32_e32 v117, v0
	v_mov_b32_e32 v118, v0
	v_mov_b32_e32 v119, v0
	v_mov_b32_e32 v72, v0
	v_mov_b32_e32 v73, v0
	v_mov_b32_e32 v74, v0
	v_mov_b32_e32 v75, v0
	v_mov_b32_e32 v76, v0
	v_mov_b32_e32 v77, v0
	v_mov_b32_e32 v78, v0
	v_mov_b32_e32 v79, v0
	v_mov_b32_e32 v88, v0
	v_mov_b32_e32 v89, v0
	v_mov_b32_e32 v90, v0
	v_mov_b32_e32 v91, v0
	v_mov_b32_e32 v92, v0
	v_mov_b32_e32 v93, v0
	v_mov_b32_e32 v94, v0
	v_mov_b32_e32 v95, v0
	v_mov_b32_e32 v104, v0
	v_mov_b32_e32 v105, v0
	v_mov_b32_e32 v106, v0
	v_mov_b32_e32 v107, v0
	v_mov_b32_e32 v108, v0
	v_mov_b32_e32 v109, v0
	v_mov_b32_e32 v110, v0
	v_mov_b32_e32 v111, v0
	v_mov_b32_e32 v120, v0
	v_mov_b32_e32 v121, v0
	v_mov_b32_e32 v122, v0
	v_mov_b32_e32 v123, v0
	v_mov_b32_e32 v124, v0
	v_mov_b32_e32 v125, v0
	v_mov_b32_e32 v126, v0
	v_mov_b32_e32 v127, v0
	s_andn2_b64 vcc, exec, s[40:41]
	s_cbranch_vccnz .LBB0_742
	s_branch .LBB0_743

.LBB0_841:
	s_lshl_b32 s60, s78, 7
	s_add_u32 s61, s24, s60
	s_addc_u32 s62, s25, 0
	s_add_u32 s63, s61, 0x100
	s_addc_u32 s79, s62, 0
	s_and_b64 s[58:59], s[48:49], exec
	s_cselect_b32 s59, s31, s79
	s_cselect_b32 s58, s35, s63
	s_add_u32 s60, s26, s60
	s_addc_u32 s63, s27, 0
	s_add_u32 s60, s60, 0x100
	s_addc_u32 s63, s63, 0
	s_and_b64 s[48:49], s[48:49], exec
	s_cselect_b32 s49, s29, s63
	s_cselect_b32 s48, s77, s60
	s_add_i32 s63, 0, 0x10000
	v_add_u32_e32 v146, s63, v132
	s_add_i32 s79, 0, 0x14000
	ds_read_b128 v[134:137], v146
	ds_read_b128 v[138:141], v146 offset:1024
	ds_read_b128 v[142:145], v146 offset:2048
	ds_read_b128 v[156:159], v146 offset:3072
	v_add_u32_e32 v146, s79, v132
	ds_read_b128 v[164:167], v146
	ds_read_b128 v[168:171], v146 offset:1024
	ds_read_b128 v[172:175], v146 offset:2048
	ds_read_b128 v[176:179], v146 offset:3072
	s_add_u32 s60, s61, 0x40080
	s_addc_u32 s61, s62, 0
	v_lshl_add_u64 v[146:147], s[60:61], 0, v[148:149]
	s_add_i32 m0, s70, 0xc000
	ds_read_b128 v[180:183], v133
	ds_read_b128 v[184:187], v133 offset:1024
	ds_read_b128 v[188:191], v133 offset:2048
	ds_read_b128 v[192:195], v133 offset:3072
	ds_read_b128 v[196:199], v133 offset:4096
	ds_read_b128 v[200:203], v133 offset:5120
	ds_read_b128 v[204:207], v133 offset:6144
	ds_read_b128 v[218:221], v133 offset:7168
	global_load_lds_dwordx4 v[146:147], off
	v_lshl_add_u64 v[146:147], s[60:61], 0, v[130:131]
	s_add_i32 m0, s70, 0xe000
	s_nop 0
	global_load_lds_dwordx4 v[146:147], off
	s_waitcnt vmcnt(8)
	s_waitcnt lgkmcnt(0)
	s_setprio 1
	s_barrier
	v_mfma_f32_16x16x32_bf16 v[124:127], v[134:137], v[180:183], v[124:127]
	v_mfma_f32_16x16x32_bf16 v[120:123], v[142:145], v[180:183], v[120:123]
	v_mfma_f32_16x16x32_bf16 v[112:115], v[134:137], v[188:191], v[112:115]
	v_mfma_f32_16x16x32_bf16 v[104:107], v[142:145], v[188:191], v[104:107]
	v_mfma_f32_16x16x32_bf16 v[92:95], v[134:137], v[196:199], v[92:95]
	v_mfma_f32_16x16x32_bf16 v[88:91], v[142:145], v[196:199], v[88:91]
	v_mfma_f32_16x16x32_bf16 v[76:79], v[134:137], v[204:207], v[76:79]
	v_mfma_f32_16x16x32_bf16 v[72:75], v[142:145], v[204:207], v[72:75]
	v_mfma_f32_16x16x32_bf16 v[124:127], v[138:141], v[184:187], v[124:127]
	v_mfma_f32_16x16x32_bf16 v[120:123], v[156:159], v[184:187], v[120:123]
	v_mfma_f32_16x16x32_bf16 v[112:115], v[138:141], v[192:195], v[112:115]
	v_mfma_f32_16x16x32_bf16 v[104:107], v[156:159], v[192:195], v[104:107]
	v_mfma_f32_16x16x32_bf16 v[92:95], v[138:141], v[200:203], v[92:95]
	v_mfma_f32_16x16x32_bf16 v[88:91], v[156:159], v[200:203], v[88:91]
	v_mfma_f32_16x16x32_bf16 v[76:79], v[138:141], v[218:221], v[76:79]
	v_mfma_f32_16x16x32_bf16 v[72:75], v[156:159], v[218:221], v[72:75]
	s_setprio 0
	s_setprio 1
	v_mfma_f32_16x16x32_bf16 v[116:119], v[164:167], v[180:183], v[116:119]
	v_mfma_f32_16x16x32_bf16 v[108:111], v[172:175], v[180:183], v[108:111]
	v_mfma_f32_16x16x32_bf16 v[100:103], v[164:167], v[188:191], v[100:103]
	v_mfma_f32_16x16x32_bf16 v[96:99], v[172:175], v[188:191], v[96:99]
	v_mfma_f32_16x16x32_bf16 v[84:87], v[164:167], v[196:199], v[84:87]
	v_mfma_f32_16x16x32_bf16 v[80:83], v[172:175], v[196:199], v[80:83]
	v_mfma_f32_16x16x32_bf16 v[68:71], v[164:167], v[204:207], v[68:71]
	v_mfma_f32_16x16x32_bf16 v[64:67], v[172:175], v[204:207], v[64:67]
	v_mfma_f32_16x16x32_bf16 v[116:119], v[168:171], v[184:187], v[116:119]
	v_mfma_f32_16x16x32_bf16 v[108:111], v[176:179], v[184:187], v[108:111]
	v_mfma_f32_16x16x32_bf16 v[100:103], v[168:171], v[192:195], v[100:103]
	v_mfma_f32_16x16x32_bf16 v[96:99], v[176:179], v[192:195], v[96:99]
	v_mfma_f32_16x16x32_bf16 v[84:87], v[168:171], v[200:203], v[84:87]
	v_mfma_f32_16x16x32_bf16 v[80:83], v[176:179], v[200:203], v[80:83]
	v_mfma_f32_16x16x32_bf16 v[68:71], v[168:171], v[218:221], v[68:71]
	v_mfma_f32_16x16x32_bf16 v[64:67], v[176:179], v[218:221], v[64:67]
	s_setprio 0
	s_barrier
	s_add_i32 s60, s63, s69
	v_lshl_add_u64 v[146:147], s[48:49], 0, v[148:149]
	s_mov_b32 m0, s60
	ds_read_b128 v[180:183], v133 offset:16384
	ds_read_b128 v[184:187], v133 offset:17408
	ds_read_b128 v[188:191], v133 offset:18432
	ds_read_b128 v[192:195], v133 offset:19456
	ds_read_b128 v[196:199], v133 offset:20480
	ds_read_b128 v[200:203], v133 offset:21504
	ds_read_b128 v[204:207], v133 offset:22528
	ds_read_b128 v[218:221], v133 offset:23552
	global_load_lds_dwordx4 v[146:147], off
	s_add_i32 m0, s60, 0x2000
	s_add_u32 s60, s48, 0x40000
	v_lshl_add_u64 v[154:155], s[48:49], 0, v[130:131]
	s_addc_u32 s61, s49, 0
	s_add_i32 s62, s79, s69
	global_load_lds_dwordx4 v[154:155], off
	v_lshl_add_u64 v[160:161], s[60:61], 0, v[148:149]
	s_mov_b32 m0, s62
	v_lshl_add_u64 v[208:209], s[58:59], 0, v[130:131]
	global_load_lds_dwordx4 v[160:161], off
	v_lshl_add_u64 v[160:161], s[60:61], 0, v[130:131]
	s_add_i32 m0, s62, 0x2000
	s_nop 0
	global_load_lds_dwordx4 v[160:161], off
	v_lshl_add_u64 v[160:161], s[58:59], 0, v[148:149]
	s_mov_b32 m0, s70
	s_nop 0
	global_load_lds_dwordx4 v[160:161], off
	s_mov_b32 m0, s71
	s_nop 0
	global_load_lds_dwordx4 v[208:209], off
	s_waitcnt vmcnt(8)
	s_waitcnt lgkmcnt(0)
	s_setprio 1
	s_barrier
	v_mfma_f32_16x16x32_bf16 v[60:63], v[134:137], v[180:183], v[60:63]
	v_mfma_f32_16x16x32_bf16 v[56:59], v[142:145], v[180:183], v[56:59]
	v_mfma_f32_16x16x32_bf16 v[44:47], v[134:137], v[188:191], v[44:47]
	v_mfma_f32_16x16x32_bf16 v[40:43], v[142:145], v[188:191], v[40:43]
	v_mfma_f32_16x16x32_bf16 v[28:31], v[134:137], v[196:199], v[28:31]
	v_mfma_f32_16x16x32_bf16 v[24:27], v[142:145], v[196:199], v[24:27]
	v_mfma_f32_16x16x32_bf16 v[12:15], v[134:137], v[204:207], v[12:15]
	v_mfma_f32_16x16x32_bf16 v[8:11], v[142:145], v[204:207], v[8:11]
	v_mfma_f32_16x16x32_bf16 v[60:63], v[138:141], v[184:187], v[60:63]
	v_mfma_f32_16x16x32_bf16 v[56:59], v[156:159], v[184:187], v[56:59]
	v_mfma_f32_16x16x32_bf16 v[44:47], v[138:141], v[192:195], v[44:47]
	v_mfma_f32_16x16x32_bf16 v[40:43], v[156:159], v[192:195], v[40:43]
	v_mfma_f32_16x16x32_bf16 v[28:31], v[138:141], v[200:203], v[28:31]
	v_mfma_f32_16x16x32_bf16 v[24:27], v[156:159], v[200:203], v[24:27]
	v_mfma_f32_16x16x32_bf16 v[12:15], v[138:141], v[218:221], v[12:15]
	v_mfma_f32_16x16x32_bf16 v[8:11], v[156:159], v[218:221], v[8:11]
	s_setprio 0
	s_setprio 1
	v_mfma_f32_16x16x32_bf16 v[52:55], v[164:167], v[180:183], v[52:55]
	v_mfma_f32_16x16x32_bf16 v[48:51], v[172:175], v[180:183], v[48:51]
	v_mfma_f32_16x16x32_bf16 v[36:39], v[164:167], v[188:191], v[36:39]
	v_mfma_f32_16x16x32_bf16 v[32:35], v[172:175], v[188:191], v[32:35]
	v_mfma_f32_16x16x32_bf16 v[20:23], v[164:167], v[196:199], v[20:23]
	v_mfma_f32_16x16x32_bf16 v[16:19], v[172:175], v[196:199], v[16:19]
	v_mfma_f32_16x16x32_bf16 v[4:7], v[164:167], v[204:207], v[4:7]
	v_mfma_f32_16x16x32_bf16 v[0:3], v[172:175], v[204:207], v[0:3]
	v_mfma_f32_16x16x32_bf16 v[52:55], v[168:171], v[184:187], v[52:55]
	v_mfma_f32_16x16x32_bf16 v[48:51], v[176:179], v[184:187], v[48:51]
	v_mfma_f32_16x16x32_bf16 v[36:39], v[168:171], v[192:195], v[36:39]
	v_mfma_f32_16x16x32_bf16 v[32:35], v[176:179], v[192:195], v[32:35]
	v_mfma_f32_16x16x32_bf16 v[20:23], v[168:171], v[200:203], v[20:23]
	v_mfma_f32_16x16x32_bf16 v[16:19], v[176:179], v[200:203], v[16:19]
	v_mfma_f32_16x16x32_bf16 v[4:7], v[168:171], v[218:221], v[4:7]
	v_mfma_f32_16x16x32_bf16 v[0:3], v[176:179], v[218:221], v[0:3]
	s_setprio 0
	s_barrier
	s_add_i32 s60, 0, 0x18000
	s_add_i32 s61, 0, 0x1c000
	v_add_u32_e32 v156, s60, v132
	v_add_u32_e32 v162, s61, v132
	ds_read_b128 v[134:137], v156
	ds_read_b128 v[138:141], v156 offset:1024
	ds_read_b128 v[142:145], v156 offset:2048
	ds_read_b128 v[156:159], v156 offset:3072
	ds_read_b128 v[164:167], v162
	ds_read_b128 v[168:171], v162 offset:1024
	ds_read_b128 v[172:175], v162 offset:2048
	ds_read_b128 v[176:179], v162 offset:3072
	s_add_u32 s58, s58, 0x40000
	s_addc_u32 s59, s59, 0
	s_mov_b32 m0, s72
	v_lshl_add_u64 v[212:213], s[58:59], 0, v[148:149]
	ds_read_b128 v[180:183], v133 offset:32768
	ds_read_b128 v[184:187], v133 offset:33792
	ds_read_b128 v[188:191], v133 offset:34816
	ds_read_b128 v[192:195], v133 offset:35840
	ds_read_b128 v[196:199], v133 offset:36864
	ds_read_b128 v[200:203], v133 offset:37888
	ds_read_b128 v[204:207], v133 offset:38912
	ds_read_b128 v[218:221], v133 offset:39936
	global_load_lds_dwordx4 v[212:213], off
	v_lshl_add_u64 v[212:213], s[58:59], 0, v[130:131]
	s_mov_b32 m0, s73
	s_nop 0
	global_load_lds_dwordx4 v[212:213], off
	s_waitcnt vmcnt(8)
	s_waitcnt lgkmcnt(0)
	s_setprio 1
	s_barrier
	v_mfma_f32_16x16x32_bf16 v[124:127], v[134:137], v[180:183], v[124:127]
	v_mfma_f32_16x16x32_bf16 v[120:123], v[142:145], v[180:183], v[120:123]
	v_mfma_f32_16x16x32_bf16 v[112:115], v[134:137], v[188:191], v[112:115]
	v_mfma_f32_16x16x32_bf16 v[104:107], v[142:145], v[188:191], v[104:107]
	v_mfma_f32_16x16x32_bf16 v[92:95], v[134:137], v[196:199], v[92:95]
	v_mfma_f32_16x16x32_bf16 v[88:91], v[142:145], v[196:199], v[88:91]
	v_mfma_f32_16x16x32_bf16 v[76:79], v[134:137], v[204:207], v[76:79]
	v_mfma_f32_16x16x32_bf16 v[72:75], v[142:145], v[204:207], v[72:75]
	v_mfma_f32_16x16x32_bf16 v[124:127], v[138:141], v[184:187], v[124:127]
	v_mfma_f32_16x16x32_bf16 v[120:123], v[156:159], v[184:187], v[120:123]
	v_mfma_f32_16x16x32_bf16 v[112:115], v[138:141], v[192:195], v[112:115]
	v_mfma_f32_16x16x32_bf16 v[104:107], v[156:159], v[192:195], v[104:107]
	v_mfma_f32_16x16x32_bf16 v[92:95], v[138:141], v[200:203], v[92:95]
	v_mfma_f32_16x16x32_bf16 v[88:91], v[156:159], v[200:203], v[88:91]
	v_mfma_f32_16x16x32_bf16 v[76:79], v[138:141], v[218:221], v[76:79]
	v_mfma_f32_16x16x32_bf16 v[72:75], v[156:159], v[218:221], v[72:75]
	s_setprio 0
	s_setprio 1
	v_mfma_f32_16x16x32_bf16 v[116:119], v[164:167], v[180:183], v[116:119]
	v_mfma_f32_16x16x32_bf16 v[108:111], v[172:175], v[180:183], v[108:111]
	v_mfma_f32_16x16x32_bf16 v[100:103], v[164:167], v[188:191], v[100:103]
	v_mfma_f32_16x16x32_bf16 v[96:99], v[172:175], v[188:191], v[96:99]
	v_mfma_f32_16x16x32_bf16 v[84:87], v[164:167], v[196:199], v[84:87]
	v_mfma_f32_16x16x32_bf16 v[80:83], v[172:175], v[196:199], v[80:83]
	v_mfma_f32_16x16x32_bf16 v[68:71], v[164:167], v[204:207], v[68:71]
	v_mfma_f32_16x16x32_bf16 v[64:67], v[172:175], v[204:207], v[64:67]
	v_mfma_f32_16x16x32_bf16 v[116:119], v[168:171], v[184:187], v[116:119]
	v_mfma_f32_16x16x32_bf16 v[108:111], v[176:179], v[184:187], v[108:111]
	v_mfma_f32_16x16x32_bf16 v[100:103], v[168:171], v[192:195], v[100:103]
	v_mfma_f32_16x16x32_bf16 v[96:99], v[176:179], v[192:195], v[96:99]
	v_mfma_f32_16x16x32_bf16 v[84:87], v[168:171], v[200:203], v[84:87]
	v_mfma_f32_16x16x32_bf16 v[80:83], v[176:179], v[200:203], v[80:83]
	v_mfma_f32_16x16x32_bf16 v[68:71], v[168:171], v[218:221], v[68:71]
	v_mfma_f32_16x16x32_bf16 v[64:67], v[176:179], v[218:221], v[64:67]
	s_setprio 0
	s_barrier
	s_add_i32 s58, s60, s69
	v_lshl_add_u64 v[146:147], v[146:147], 0, s[0:1]
	s_mov_b32 m0, s58
	ds_read_b128 v[180:183], v133 offset:49152
	ds_read_b128 v[184:187], v133 offset:50176
	ds_read_b128 v[188:191], v133 offset:51200
	ds_read_b128 v[192:195], v133 offset:52224
	ds_read_b128 v[196:199], v133 offset:53248
	ds_read_b128 v[200:203], v133 offset:54272
	ds_read_b128 v[204:207], v133 offset:55296
	ds_read_b128 v[218:221], v133 offset:56320
	global_load_lds_dwordx4 v[146:147], off
	s_add_i32 m0, s58, 0x2000
	s_add_u32 s48, s48, 0x40080
	v_lshl_add_u64 v[146:147], v[154:155], 0, s[0:1]
	s_addc_u32 s49, s49, 0
	s_add_i32 s58, s61, s69
	global_load_lds_dwordx4 v[146:147], off
	v_lshl_add_u64 v[146:147], s[48:49], 0, v[148:149]
	s_mov_b32 m0, s58
	s_nop 0
	global_load_lds_dwordx4 v[146:147], off
	v_lshl_add_u64 v[146:147], s[48:49], 0, v[130:131]
	s_add_i32 m0, s58, 0x2000
	s_nop 0
	global_load_lds_dwordx4 v[146:147], off
	v_lshl_add_u64 v[146:147], v[160:161], 0, s[0:1]
	s_mov_b32 m0, s74
	s_nop 0
	global_load_lds_dwordx4 v[146:147], off
	v_lshl_add_u64 v[146:147], v[208:209], 0, s[0:1]
	s_mov_b32 m0, s75
	s_nop 0
	global_load_lds_dwordx4 v[146:147], off
	s_waitcnt vmcnt(8)
	s_waitcnt lgkmcnt(0)
	s_setprio 1
	s_barrier
	v_mfma_f32_16x16x32_bf16 v[60:63], v[134:137], v[180:183], v[60:63]
	v_mfma_f32_16x16x32_bf16 v[56:59], v[142:145], v[180:183], v[56:59]
	v_mfma_f32_16x16x32_bf16 v[44:47], v[134:137], v[188:191], v[44:47]
	v_mfma_f32_16x16x32_bf16 v[40:43], v[142:145], v[188:191], v[40:43]
	v_mfma_f32_16x16x32_bf16 v[28:31], v[134:137], v[196:199], v[28:31]
	v_mfma_f32_16x16x32_bf16 v[24:27], v[142:145], v[196:199], v[24:27]
	v_mfma_f32_16x16x32_bf16 v[12:15], v[134:137], v[204:207], v[12:15]
	v_mfma_f32_16x16x32_bf16 v[8:11], v[142:145], v[204:207], v[8:11]
	v_mfma_f32_16x16x32_bf16 v[60:63], v[138:141], v[184:187], v[60:63]
	v_mfma_f32_16x16x32_bf16 v[56:59], v[156:159], v[184:187], v[56:59]
	v_mfma_f32_16x16x32_bf16 v[44:47], v[138:141], v[192:195], v[44:47]
	v_mfma_f32_16x16x32_bf16 v[40:43], v[156:159], v[192:195], v[40:43]
	v_mfma_f32_16x16x32_bf16 v[28:31], v[138:141], v[200:203], v[28:31]
	v_mfma_f32_16x16x32_bf16 v[24:27], v[156:159], v[200:203], v[24:27]
	v_mfma_f32_16x16x32_bf16 v[12:15], v[138:141], v[218:221], v[12:15]
	v_mfma_f32_16x16x32_bf16 v[8:11], v[156:159], v[218:221], v[8:11]
	s_setprio 0
	s_setprio 1
	v_mfma_f32_16x16x32_bf16 v[52:55], v[164:167], v[180:183], v[52:55]
	v_mfma_f32_16x16x32_bf16 v[48:51], v[172:175], v[180:183], v[48:51]
	v_mfma_f32_16x16x32_bf16 v[36:39], v[164:167], v[188:191], v[36:39]
	v_mfma_f32_16x16x32_bf16 v[32:35], v[172:175], v[188:191], v[32:35]
	v_mfma_f32_16x16x32_bf16 v[20:23], v[164:167], v[196:199], v[20:23]
	v_mfma_f32_16x16x32_bf16 v[16:19], v[172:175], v[196:199], v[16:19]
	v_mfma_f32_16x16x32_bf16 v[4:7], v[164:167], v[204:207], v[4:7]
	v_mfma_f32_16x16x32_bf16 v[0:3], v[172:175], v[204:207], v[0:3]
	v_mfma_f32_16x16x32_bf16 v[52:55], v[168:171], v[184:187], v[52:55]
	v_mfma_f32_16x16x32_bf16 v[48:51], v[176:179], v[184:187], v[48:51]
	v_mfma_f32_16x16x32_bf16 v[36:39], v[168:171], v[192:195], v[36:39]
	v_mfma_f32_16x16x32_bf16 v[32:35], v[176:179], v[192:195], v[32:35]
	v_mfma_f32_16x16x32_bf16 v[20:23], v[168:171], v[200:203], v[20:23]
	v_mfma_f32_16x16x32_bf16 v[16:19], v[176:179], v[200:203], v[16:19]
	v_mfma_f32_16x16x32_bf16 v[4:7], v[168:171], v[218:221], v[4:7]
	v_mfma_f32_16x16x32_bf16 v[0:3], v[176:179], v[218:221], v[0:3]
	s_setprio 0
	s_barrier
	s_add_i32 s48, s78, 2
	s_cmp_gt_u32 s78, 13
	s_cbranch_scc1 .LBB0_843
	s_mov_b32 s78, s48
	s_branch .LBB0_820

.LBB0_903:
	s_add_u32 s36, s22, s34
	s_addc_u32 s37, s23, s35
	s_add_u32 s36, s36, 0x100
	s_addc_u32 s37, s37, 0
	s_add_u32 s71, s64, s34
	s_addc_u32 s72, s65, s35
	s_add_i32 s73, 0, 0x10000
	s_cmpk_eq_i32 s34, 0x700
	s_cselect_b32 s39, s27, s37
	s_cselect_b32 s38, s68, s36
	v_add_u32_e32 v146, s73, v140
	s_cselect_b32 s37, s25, s72
	s_cselect_b32 s36, s69, s71
	s_add_i32 s71, 0, 0x14000
	ds_read_b128 v[142:145], v146
	ds_read_b128 v[156:159], v146 offset:1024
	ds_read_b128 v[160:163], v146 offset:2048
	ds_read_b128 v[164:167], v146 offset:3072
	v_add_u32_e32 v146, s71, v140
	ds_read_b128 v[168:171], v146
	ds_read_b128 v[172:175], v146 offset:1024
	ds_read_b128 v[176:179], v146 offset:2048
	ds_read_b128 v[184:187], v146 offset:3072
	v_lshl_add_u64 v[146:147], v[138:139], 0, s[34:35]
	s_add_i32 m0, s47, 0xc000
	ds_read_b128 v[188:191], v141
	ds_read_b128 v[192:195], v141 offset:1024
	ds_read_b128 v[196:199], v141 offset:2048
	ds_read_b128 v[200:203], v141 offset:3072
	ds_read_b128 v[204:207], v141 offset:4096
	ds_read_b128 v[218:221], v141 offset:5120
	ds_read_b128 v[222:225], v141 offset:6144
	ds_read_b128 v[226:229], v141 offset:7168
	global_load_lds_dwordx4 v[146:147], off
	v_lshl_add_u64 v[146:147], v[134:135], 0, s[34:35]
	s_add_i32 m0, s47, 0xe000
	s_nop 0
	global_load_lds_dwordx4 v[146:147], off
	s_waitcnt vmcnt(8)
	s_waitcnt lgkmcnt(0)
	s_setprio 1
	s_barrier
	v_mfma_f32_16x16x32_bf16 v[48:51], v[142:145], v[188:191], v[48:51]
	v_mfma_f32_16x16x32_bf16 v[52:55], v[160:163], v[188:191], v[52:55]
	v_mfma_f32_16x16x32_bf16 v[128:131], v[142:145], v[196:199], v[128:131]
	v_mfma_f32_16x16x32_bf16 v[64:67], v[160:163], v[196:199], v[64:67]
	v_mfma_f32_16x16x32_bf16 v[96:99], v[142:145], v[204:207], v[96:99]
	v_mfma_f32_16x16x32_bf16 v[100:103], v[160:163], v[204:207], v[100:103]
	v_mfma_f32_16x16x32_bf16 v[120:123], v[142:145], v[222:225], v[120:123]
	v_mfma_f32_16x16x32_bf16 v[124:127], v[160:163], v[222:225], v[124:127]
	v_mfma_f32_16x16x32_bf16 v[48:51], v[156:159], v[192:195], v[48:51]
	v_mfma_f32_16x16x32_bf16 v[52:55], v[164:167], v[192:195], v[52:55]
	v_mfma_f32_16x16x32_bf16 v[128:131], v[156:159], v[200:203], v[128:131]
	v_mfma_f32_16x16x32_bf16 v[64:67], v[164:167], v[200:203], v[64:67]
	v_mfma_f32_16x16x32_bf16 v[96:99], v[156:159], v[218:221], v[96:99]
	v_mfma_f32_16x16x32_bf16 v[100:103], v[164:167], v[218:221], v[100:103]
	v_mfma_f32_16x16x32_bf16 v[120:123], v[156:159], v[226:229], v[120:123]
	v_mfma_f32_16x16x32_bf16 v[124:127], v[164:167], v[226:229], v[124:127]
	s_setprio 0
	s_setprio 1
	v_mfma_f32_16x16x32_bf16 v[56:59], v[168:171], v[188:191], v[56:59]
	v_mfma_f32_16x16x32_bf16 v[60:63], v[176:179], v[188:191], v[60:63]
	v_mfma_f32_16x16x32_bf16 v[72:75], v[168:171], v[196:199], v[72:75]
	v_mfma_f32_16x16x32_bf16 v[76:79], v[176:179], v[196:199], v[76:79]
	v_mfma_f32_16x16x32_bf16 v[104:107], v[168:171], v[204:207], v[104:107]
	v_mfma_f32_16x16x32_bf16 v[108:111], v[176:179], v[204:207], v[108:111]
	v_mfma_f32_16x16x32_bf16 v[116:119], v[168:171], v[222:225], v[116:119]
	v_mfma_f32_16x16x32_bf16 v[112:115], v[176:179], v[222:225], v[112:115]
	v_mfma_f32_16x16x32_bf16 v[56:59], v[172:175], v[192:195], v[56:59]
	v_mfma_f32_16x16x32_bf16 v[60:63], v[184:187], v[192:195], v[60:63]
	v_mfma_f32_16x16x32_bf16 v[72:75], v[172:175], v[200:203], v[72:75]
	v_mfma_f32_16x16x32_bf16 v[76:79], v[184:187], v[200:203], v[76:79]
	v_mfma_f32_16x16x32_bf16 v[104:107], v[172:175], v[218:221], v[104:107]
	v_mfma_f32_16x16x32_bf16 v[108:111], v[184:187], v[218:221], v[108:111]
	v_mfma_f32_16x16x32_bf16 v[116:119], v[172:175], v[226:229], v[116:119]
	v_mfma_f32_16x16x32_bf16 v[112:115], v[184:187], v[226:229], v[112:115]
	s_setprio 0
	s_barrier
	s_add_i32 s72, s73, s46
	v_lshl_add_u64 v[146:147], s[36:37], 0, v[148:149]
	s_mov_b32 m0, s72
	ds_read_b128 v[188:191], v141 offset:16384
	ds_read_b128 v[192:195], v141 offset:17408
	ds_read_b128 v[196:199], v141 offset:18432
	ds_read_b128 v[200:203], v141 offset:19456
	ds_read_b128 v[204:207], v141 offset:20480
	ds_read_b128 v[218:221], v141 offset:21504
	ds_read_b128 v[222:225], v141 offset:22528
	ds_read_b128 v[226:229], v141 offset:23552
	global_load_lds_dwordx4 v[146:147], off
	s_add_i32 m0, s72, 0x2000
	s_add_u32 s72, s36, 0x40000
	v_lshl_add_u64 v[154:155], s[36:37], 0, v[80:81]
	s_addc_u32 s73, s37, 0
	s_add_i32 s71, s71, s46
	global_load_lds_dwordx4 v[154:155], off
	v_lshl_add_u64 v[180:181], s[72:73], 0, v[148:149]
	s_mov_b32 m0, s71
	v_lshl_add_u64 v[208:209], s[38:39], 0, v[80:81]
	global_load_lds_dwordx4 v[180:181], off
	v_lshl_add_u64 v[180:181], s[72:73], 0, v[80:81]
	s_add_i32 m0, s71, 0x2000
	s_nop 0
	global_load_lds_dwordx4 v[180:181], off
	v_lshl_add_u64 v[180:181], s[38:39], 0, v[148:149]
	s_mov_b32 m0, s47
	s_nop 0
	global_load_lds_dwordx4 v[180:181], off
	s_mov_b32 m0, s49
	s_nop 0
	global_load_lds_dwordx4 v[208:209], off
	s_waitcnt vmcnt(8)
	s_waitcnt lgkmcnt(0)
	s_setprio 1
	s_barrier
	v_mfma_f32_16x16x32_bf16 v[92:95], v[142:145], v[188:191], v[92:95]
	v_mfma_f32_16x16x32_bf16 v[88:91], v[160:163], v[188:191], v[88:91]
	v_mfma_f32_16x16x32_bf16 v[44:47], v[142:145], v[196:199], v[44:47]
	v_mfma_f32_16x16x32_bf16 v[40:43], v[160:163], v[196:199], v[40:43]
	v_mfma_f32_16x16x32_bf16 v[28:31], v[142:145], v[204:207], v[28:31]
	v_mfma_f32_16x16x32_bf16 v[24:27], v[160:163], v[204:207], v[24:27]
	v_mfma_f32_16x16x32_bf16 v[12:15], v[142:145], v[222:225], v[12:15]
	v_mfma_f32_16x16x32_bf16 v[8:11], v[160:163], v[222:225], v[8:11]
	v_mfma_f32_16x16x32_bf16 v[92:95], v[156:159], v[192:195], v[92:95]
	v_mfma_f32_16x16x32_bf16 v[88:91], v[164:167], v[192:195], v[88:91]
	v_mfma_f32_16x16x32_bf16 v[44:47], v[156:159], v[200:203], v[44:47]
	v_mfma_f32_16x16x32_bf16 v[40:43], v[164:167], v[200:203], v[40:43]
	v_mfma_f32_16x16x32_bf16 v[28:31], v[156:159], v[218:221], v[28:31]
	v_mfma_f32_16x16x32_bf16 v[24:27], v[164:167], v[218:221], v[24:27]
	v_mfma_f32_16x16x32_bf16 v[12:15], v[156:159], v[226:229], v[12:15]
	v_mfma_f32_16x16x32_bf16 v[8:11], v[164:167], v[226:229], v[8:11]
	s_setprio 0
	s_setprio 1
	v_mfma_f32_16x16x32_bf16 v[84:87], v[168:171], v[188:191], v[84:87]
	v_mfma_f32_16x16x32_bf16 v[68:71], v[176:179], v[188:191], v[68:71]
	v_mfma_f32_16x16x32_bf16 v[36:39], v[168:171], v[196:199], v[36:39]
	v_mfma_f32_16x16x32_bf16 v[32:35], v[176:179], v[196:199], v[32:35]
	v_mfma_f32_16x16x32_bf16 v[20:23], v[168:171], v[204:207], v[20:23]
	v_mfma_f32_16x16x32_bf16 v[16:19], v[176:179], v[204:207], v[16:19]
	v_mfma_f32_16x16x32_bf16 v[4:7], v[168:171], v[222:225], v[4:7]
	v_mfma_f32_16x16x32_bf16 v[0:3], v[176:179], v[222:225], v[0:3]
	v_mfma_f32_16x16x32_bf16 v[84:87], v[172:175], v[192:195], v[84:87]
	v_mfma_f32_16x16x32_bf16 v[68:71], v[184:187], v[192:195], v[68:71]
	v_mfma_f32_16x16x32_bf16 v[36:39], v[172:175], v[200:203], v[36:39]
	v_mfma_f32_16x16x32_bf16 v[32:35], v[184:187], v[200:203], v[32:35]
	v_mfma_f32_16x16x32_bf16 v[20:23], v[172:175], v[218:221], v[20:23]
	v_mfma_f32_16x16x32_bf16 v[16:19], v[184:187], v[218:221], v[16:19]
	v_mfma_f32_16x16x32_bf16 v[4:7], v[172:175], v[226:229], v[4:7]
	v_mfma_f32_16x16x32_bf16 v[0:3], v[184:187], v[226:229], v[0:3]
	s_setprio 0
	s_barrier
	s_add_i32 s71, 0, 0x18000
	s_add_i32 s72, 0, 0x1c000
	v_add_u32_e32 v164, s71, v140
	v_add_u32_e32 v183, s72, v140
	ds_read_b128 v[142:145], v164
	ds_read_b128 v[156:159], v164 offset:1024
	ds_read_b128 v[160:163], v164 offset:2048
	ds_read_b128 v[164:167], v164 offset:3072
	ds_read_b128 v[168:171], v183
	ds_read_b128 v[172:175], v183 offset:1024
	ds_read_b128 v[176:179], v183 offset:2048
	ds_read_b128 v[184:187], v183 offset:3072
	s_add_u32 s38, s38, 0x40000
	s_addc_u32 s39, s39, 0
	s_mov_b32 m0, s58
	v_lshl_add_u64 v[212:213], s[38:39], 0, v[148:149]
	ds_read_b128 v[188:191], v141 offset:32768
	ds_read_b128 v[192:195], v141 offset:33792
	ds_read_b128 v[196:199], v141 offset:34816
	ds_read_b128 v[200:203], v141 offset:35840
	ds_read_b128 v[204:207], v141 offset:36864
	ds_read_b128 v[218:221], v141 offset:37888
	ds_read_b128 v[222:225], v141 offset:38912
	ds_read_b128 v[226:229], v141 offset:39936
	global_load_lds_dwordx4 v[212:213], off
	v_lshl_add_u64 v[212:213], s[38:39], 0, v[80:81]
	s_mov_b32 m0, s59
	s_nop 0
	global_load_lds_dwordx4 v[212:213], off
	s_waitcnt vmcnt(8)
	s_waitcnt lgkmcnt(0)
	s_setprio 1
	s_barrier
	v_mfma_f32_16x16x32_bf16 v[48:51], v[142:145], v[188:191], v[48:51]
	v_mfma_f32_16x16x32_bf16 v[52:55], v[160:163], v[188:191], v[52:55]
	v_mfma_f32_16x16x32_bf16 v[128:131], v[142:145], v[196:199], v[128:131]
	v_mfma_f32_16x16x32_bf16 v[64:67], v[160:163], v[196:199], v[64:67]
	v_mfma_f32_16x16x32_bf16 v[96:99], v[142:145], v[204:207], v[96:99]
	v_mfma_f32_16x16x32_bf16 v[100:103], v[160:163], v[204:207], v[100:103]
	v_mfma_f32_16x16x32_bf16 v[120:123], v[142:145], v[222:225], v[120:123]
	v_mfma_f32_16x16x32_bf16 v[124:127], v[160:163], v[222:225], v[124:127]
	v_mfma_f32_16x16x32_bf16 v[48:51], v[156:159], v[192:195], v[48:51]
	v_mfma_f32_16x16x32_bf16 v[52:55], v[164:167], v[192:195], v[52:55]
	v_mfma_f32_16x16x32_bf16 v[128:131], v[156:159], v[200:203], v[128:131]
	v_mfma_f32_16x16x32_bf16 v[64:67], v[164:167], v[200:203], v[64:67]
	v_mfma_f32_16x16x32_bf16 v[96:99], v[156:159], v[218:221], v[96:99]
	v_mfma_f32_16x16x32_bf16 v[100:103], v[164:167], v[218:221], v[100:103]
	v_mfma_f32_16x16x32_bf16 v[120:123], v[156:159], v[226:229], v[120:123]
	v_mfma_f32_16x16x32_bf16 v[124:127], v[164:167], v[226:229], v[124:127]
	s_setprio 0
	s_setprio 1
	v_mfma_f32_16x16x32_bf16 v[56:59], v[168:171], v[188:191], v[56:59]
	v_mfma_f32_16x16x32_bf16 v[60:63], v[176:179], v[188:191], v[60:63]
	v_mfma_f32_16x16x32_bf16 v[72:75], v[168:171], v[196:199], v[72:75]
	v_mfma_f32_16x16x32_bf16 v[76:79], v[176:179], v[196:199], v[76:79]
	v_mfma_f32_16x16x32_bf16 v[104:107], v[168:171], v[204:207], v[104:107]
	v_mfma_f32_16x16x32_bf16 v[108:111], v[176:179], v[204:207], v[108:111]
	v_mfma_f32_16x16x32_bf16 v[116:119], v[168:171], v[222:225], v[116:119]
	v_mfma_f32_16x16x32_bf16 v[112:115], v[176:179], v[222:225], v[112:115]
	v_mfma_f32_16x16x32_bf16 v[56:59], v[172:175], v[192:195], v[56:59]
	v_mfma_f32_16x16x32_bf16 v[60:63], v[184:187], v[192:195], v[60:63]
	v_mfma_f32_16x16x32_bf16 v[72:75], v[172:175], v[200:203], v[72:75]
	v_mfma_f32_16x16x32_bf16 v[76:79], v[184:187], v[200:203], v[76:79]
	v_mfma_f32_16x16x32_bf16 v[104:107], v[172:175], v[218:221], v[104:107]
	v_mfma_f32_16x16x32_bf16 v[108:111], v[184:187], v[218:221], v[108:111]
	v_mfma_f32_16x16x32_bf16 v[116:119], v[172:175], v[226:229], v[116:119]
	v_mfma_f32_16x16x32_bf16 v[112:115], v[184:187], v[226:229], v[112:115]
	s_setprio 0
	s_barrier
	s_add_i32 s38, s71, s46
	v_lshl_add_u64 v[146:147], v[146:147], 0, s[0:1]
	s_mov_b32 m0, s38
	ds_read_b128 v[188:191], v141 offset:49152
	ds_read_b128 v[192:195], v141 offset:50176
	ds_read_b128 v[196:199], v141 offset:51200
	ds_read_b128 v[200:203], v141 offset:52224
	ds_read_b128 v[204:207], v141 offset:53248
	ds_read_b128 v[218:221], v141 offset:54272
	ds_read_b128 v[222:225], v141 offset:55296
	ds_read_b128 v[226:229], v141 offset:56320
	global_load_lds_dwordx4 v[146:147], off
	s_add_i32 m0, s38, 0x2000
	s_add_u32 s36, s36, 0x40080
	v_lshl_add_u64 v[146:147], v[154:155], 0, s[0:1]
	s_addc_u32 s37, s37, 0
	s_add_i32 s38, s72, s46
	global_load_lds_dwordx4 v[146:147], off
	v_lshl_add_u64 v[146:147], s[36:37], 0, v[148:149]
	s_mov_b32 m0, s38
	s_nop 0
	global_load_lds_dwordx4 v[146:147], off
	v_lshl_add_u64 v[146:147], s[36:37], 0, v[80:81]
	s_add_i32 m0, s38, 0x2000
	s_nop 0
	global_load_lds_dwordx4 v[146:147], off
	v_lshl_add_u64 v[146:147], v[180:181], 0, s[0:1]
	s_mov_b32 m0, s60
	s_nop 0
	global_load_lds_dwordx4 v[146:147], off
	v_lshl_add_u64 v[146:147], v[208:209], 0, s[0:1]
	s_mov_b32 m0, s61
	s_nop 0
	global_load_lds_dwordx4 v[146:147], off
	s_waitcnt vmcnt(8)
	s_waitcnt lgkmcnt(0)
	s_setprio 1
	s_barrier
	v_mfma_f32_16x16x32_bf16 v[92:95], v[142:145], v[188:191], v[92:95]
	v_mfma_f32_16x16x32_bf16 v[88:91], v[160:163], v[188:191], v[88:91]
	v_mfma_f32_16x16x32_bf16 v[44:47], v[142:145], v[196:199], v[44:47]
	v_mfma_f32_16x16x32_bf16 v[40:43], v[160:163], v[196:199], v[40:43]
	v_mfma_f32_16x16x32_bf16 v[28:31], v[142:145], v[204:207], v[28:31]
	v_mfma_f32_16x16x32_bf16 v[24:27], v[160:163], v[204:207], v[24:27]
	v_mfma_f32_16x16x32_bf16 v[12:15], v[142:145], v[222:225], v[12:15]
	v_mfma_f32_16x16x32_bf16 v[8:11], v[160:163], v[222:225], v[8:11]
	v_mfma_f32_16x16x32_bf16 v[92:95], v[156:159], v[192:195], v[92:95]
	v_mfma_f32_16x16x32_bf16 v[88:91], v[164:167], v[192:195], v[88:91]
	v_mfma_f32_16x16x32_bf16 v[44:47], v[156:159], v[200:203], v[44:47]
	v_mfma_f32_16x16x32_bf16 v[40:43], v[164:167], v[200:203], v[40:43]
	v_mfma_f32_16x16x32_bf16 v[28:31], v[156:159], v[218:221], v[28:31]
	v_mfma_f32_16x16x32_bf16 v[24:27], v[164:167], v[218:221], v[24:27]
	v_mfma_f32_16x16x32_bf16 v[12:15], v[156:159], v[226:229], v[12:15]
	v_mfma_f32_16x16x32_bf16 v[8:11], v[164:167], v[226:229], v[8:11]
	s_setprio 0
	s_setprio 1
	v_mfma_f32_16x16x32_bf16 v[84:87], v[168:171], v[188:191], v[84:87]
	v_mfma_f32_16x16x32_bf16 v[68:71], v[176:179], v[188:191], v[68:71]
	v_mfma_f32_16x16x32_bf16 v[36:39], v[168:171], v[196:199], v[36:39]
	v_mfma_f32_16x16x32_bf16 v[32:35], v[176:179], v[196:199], v[32:35]
	v_mfma_f32_16x16x32_bf16 v[20:23], v[168:171], v[204:207], v[20:23]
	v_mfma_f32_16x16x32_bf16 v[16:19], v[176:179], v[204:207], v[16:19]
	v_mfma_f32_16x16x32_bf16 v[4:7], v[168:171], v[222:225], v[4:7]
	v_mfma_f32_16x16x32_bf16 v[0:3], v[176:179], v[222:225], v[0:3]
	v_mfma_f32_16x16x32_bf16 v[84:87], v[172:175], v[192:195], v[84:87]
	v_mfma_f32_16x16x32_bf16 v[68:71], v[184:187], v[192:195], v[68:71]
	v_mfma_f32_16x16x32_bf16 v[36:39], v[172:175], v[200:203], v[36:39]
	v_mfma_f32_16x16x32_bf16 v[32:35], v[184:187], v[200:203], v[32:35]
	v_mfma_f32_16x16x32_bf16 v[20:23], v[172:175], v[218:221], v[20:23]
	v_mfma_f32_16x16x32_bf16 v[16:19], v[184:187], v[218:221], v[16:19]
	v_mfma_f32_16x16x32_bf16 v[4:7], v[172:175], v[226:229], v[4:7]
	v_mfma_f32_16x16x32_bf16 v[0:3], v[184:187], v[226:229], v[0:3]
	s_setprio 0
	s_barrier
	s_add_i32 s70, s70, 2
	s_add_u32 s34, s34, 0x100
	s_addc_u32 s35, s35, 0
	s_cmp_gt_u32 s70, 13
	s_cbranch_scc0 .LBB0_903
	s_add_u32 s34, s64, 0xffffff00
	s_addc_u32 s35, s65, -1
	s_andn2_b64 vcc, exec, s[44:45]
	s_cbranch_vccnz .LBB0_906
	v_mov_b32_e32 v0, 0
	s_mov_b32 s6, s24
	s_mov_b32 s4, s26
	s_mov_b64 s[22:23], s[30:31]
	s_mov_b32 s62, s63
	v_mov_b32_e32 v1, v0
	v_mov_b32_e32 v2, v0
	v_mov_b32_e32 v3, v0
	v_mov_b32_e32 v4, v0
	v_mov_b32_e32 v5, v0
	v_mov_b32_e32 v6, v0
	v_mov_b32_e32 v7, v0
	v_mov_b32_e32 v16, v0
	v_mov_b32_e32 v17, v0
	v_mov_b32_e32 v18, v0
	v_mov_b32_e32 v19, v0
	v_mov_b32_e32 v20, v0
	v_mov_b32_e32 v21, v0
	v_mov_b32_e32 v22, v0
	v_mov_b32_e32 v23, v0
	v_mov_b32_e32 v32, v0
	v_mov_b32_e32 v33, v0
	v_mov_b32_e32 v34, v0
	v_mov_b32_e32 v35, v0
	v_mov_b32_e32 v36, v0
	v_mov_b32_e32 v37, v0
	v_mov_b32_e32 v38, v0
	v_mov_b32_e32 v39, v0
	v_mov_b32_e32 v68, v0
	v_mov_b32_e32 v69, v0
	v_mov_b32_e32 v70, v0
	v_mov_b32_e32 v71, v0
	v_mov_b32_e32 v84, v0
	v_mov_b32_e32 v85, v0
	v_mov_b32_e32 v86, v0
	v_mov_b32_e32 v87, v0
	v_mov_b32_e32 v8, v0
	v_mov_b32_e32 v9, v0
	v_mov_b32_e32 v10, v0
	v_mov_b32_e32 v11, v0
	v_mov_b32_e32 v12, v0
	v_mov_b32_e32 v13, v0
	v_mov_b32_e32 v14, v0
	v_mov_b32_e32 v15, v0
	v_mov_b32_e32 v24, v0
	v_mov_b32_e32 v25, v0
	v_mov_b32_e32 v26, v0
	v_mov_b32_e32 v27, v0
	v_mov_b32_e32 v28, v0
	v_mov_b32_e32 v29, v0
	v_mov_b32_e32 v30, v0
	v_mov_b32_e32 v31, v0
	v_mov_b32_e32 v40, v0
	v_mov_b32_e32 v41, v0
	v_mov_b32_e32 v42, v0
	v_mov_b32_e32 v43, v0
	v_mov_b32_e32 v44, v0
	v_mov_b32_e32 v45, v0
	v_mov_b32_e32 v46, v0
	v_mov_b32_e32 v47, v0
	v_mov_b32_e32 v88, v0
	v_mov_b32_e32 v89, v0
	v_mov_b32_e32 v90, v0
	v_mov_b32_e32 v91, v0
	v_mov_b32_e32 v92, v0
	v_mov_b32_e32 v93, v0
	v_mov_b32_e32 v94, v0
	v_mov_b32_e32 v95, v0
	v_mov_b32_e32 v112, v0
	v_mov_b32_e32 v113, v0
	v_mov_b32_e32 v114, v0
	v_mov_b32_e32 v115, v0
	v_mov_b32_e32 v116, v0
	v_mov_b32_e32 v117, v0
	v_mov_b32_e32 v118, v0
	v_mov_b32_e32 v119, v0
	v_mov_b32_e32 v108, v0
	v_mov_b32_e32 v109, v0
	v_mov_b32_e32 v110, v0
	v_mov_b32_e32 v111, v0
	v_mov_b32_e32 v104, v0
	v_mov_b32_e32 v105, v0
	v_mov_b32_e32 v106, v0
	v_mov_b32_e32 v107, v0
	v_mov_b32_e32 v76, v0
	v_mov_b32_e32 v77, v0
	v_mov_b32_e32 v78, v0
	v_mov_b32_e32 v79, v0
	v_mov_b32_e32 v72, v0
	v_mov_b32_e32 v73, v0
	v_mov_b32_e32 v74, v0
	v_mov_b32_e32 v75, v0
	v_mov_b32_e32 v60, v0
	v_mov_b32_e32 v61, v0
	v_mov_b32_e32 v62, v0
	v_mov_b32_e32 v63, v0
	v_mov_b32_e32 v56, v0
	v_mov_b32_e32 v57, v0
	v_mov_b32_e32 v58, v0
	v_mov_b32_e32 v59, v0
	v_mov_b32_e32 v124, v0
	v_mov_b32_e32 v125, v0
	v_mov_b32_e32 v126, v0
	v_mov_b32_e32 v127, v0
	v_mov_b32_e32 v120, v0
	v_mov_b32_e32 v121, v0
	v_mov_b32_e32 v122, v0
	v_mov_b32_e32 v123, v0
	v_mov_b32_e32 v100, v0
	v_mov_b32_e32 v101, v0
	v_mov_b32_e32 v102, v0
	v_mov_b32_e32 v103, v0
	v_mov_b32_e32 v96, v0
	v_mov_b32_e32 v97, v0
	v_mov_b32_e32 v98, v0
	v_mov_b32_e32 v99, v0
	v_mov_b32_e32 v64, v0
	v_mov_b32_e32 v65, v0
	v_mov_b32_e32 v66, v0
	v_mov_b32_e32 v67, v0
	v_mov_b32_e32 v128, v0
	v_mov_b32_e32 v129, v0
	v_mov_b32_e32 v130, v0
	v_mov_b32_e32 v131, v0
	v_mov_b32_e32 v52, v0
	v_mov_b32_e32 v53, v0
	v_mov_b32_e32 v54, v0
	v_mov_b32_e32 v55, v0
	v_mov_b32_e32 v48, v0
	v_mov_b32_e32 v49, v0
	v_mov_b32_e32 v50, v0
	v_mov_b32_e32 v51, v0
	s_andn2_b64 vcc, exec, s[42:43]
	s_cbranch_vccnz .LBB0_907
	s_branch .LBB0_908

.LBB0_985:
	s_add_u32 s24, s44, s22
	s_addc_u32 s25, s45, s23
	s_add_u32 s24, s24, 0x3e00100
	s_addc_u32 s25, s25, 0
	s_add_u32 s47, s42, s22
	s_addc_u32 s48, s43, s23
	s_add_i32 s49, 0, 0x10000
	s_cmpk_eq_i32 s22, 0x700
	s_cselect_b32 s27, s7, s25
	s_cselect_b32 s26, s6, s24
	v_add_u32_e32 v137, s49, v135
	s_cselect_b32 s25, s5, s48
	s_cselect_b32 s24, s4, s47
	s_add_i32 s47, 0, 0x14000
	ds_read_b128 v[138:141], v137
	ds_read_b128 v[142:145], v137 offset:1024
	ds_read_b128 v[156:159], v137 offset:2048
	ds_read_b128 v[162:165], v137 offset:3072
	v_add_u32_e32 v137, s47, v135
	ds_read_b128 v[166:169], v137
	ds_read_b128 v[170:173], v137 offset:1024
	ds_read_b128 v[176:179], v137 offset:2048
	ds_read_b128 v[180:183], v137 offset:3072
	v_lshl_add_u64 v[146:147], v[132:133], 0, s[22:23]
	s_add_i32 m0, s34, 0xc000
	ds_read_b128 v[184:187], v136
	ds_read_b128 v[188:191], v136 offset:1024
	ds_read_b128 v[192:195], v136 offset:2048
	ds_read_b128 v[196:199], v136 offset:3072
	ds_read_b128 v[200:203], v136 offset:4096
	ds_read_b128 v[204:207], v136 offset:5120
	ds_read_b128 v[218:221], v136 offset:6144
	ds_read_b128 v[222:225], v136 offset:7168
	global_load_lds_dwordx4 v[146:147], off
	v_lshl_add_u64 v[146:147], v[130:131], 0, s[22:23]
	s_add_i32 m0, s34, 0xe000
	s_nop 0
	global_load_lds_dwordx4 v[146:147], off
	s_waitcnt vmcnt(8)
	s_waitcnt lgkmcnt(0)
	s_setprio 1
	s_barrier
	v_mfma_f32_16x16x32_bf16 v[16:19], v[138:141], v[184:187], v[16:19]
	v_mfma_f32_16x16x32_bf16 v[20:23], v[156:159], v[184:187], v[20:23]
	v_mfma_f32_16x16x32_bf16 v[36:39], v[138:141], v[192:195], v[36:39]
	v_mfma_f32_16x16x32_bf16 v[40:43], v[156:159], v[192:195], v[40:43]
	v_mfma_f32_16x16x32_bf16 v[64:67], v[138:141], v[200:203], v[64:67]
	v_mfma_f32_16x16x32_bf16 v[68:71], v[156:159], v[200:203], v[68:71]
	v_mfma_f32_16x16x32_bf16 v[96:99], v[138:141], v[218:221], v[96:99]
	v_mfma_f32_16x16x32_bf16 v[100:103], v[156:159], v[218:221], v[100:103]
	v_mfma_f32_16x16x32_bf16 v[16:19], v[142:145], v[188:191], v[16:19]
	v_mfma_f32_16x16x32_bf16 v[20:23], v[162:165], v[188:191], v[20:23]
	v_mfma_f32_16x16x32_bf16 v[36:39], v[142:145], v[196:199], v[36:39]
	v_mfma_f32_16x16x32_bf16 v[40:43], v[162:165], v[196:199], v[40:43]
	v_mfma_f32_16x16x32_bf16 v[64:67], v[142:145], v[204:207], v[64:67]
	v_mfma_f32_16x16x32_bf16 v[68:71], v[162:165], v[204:207], v[68:71]
	v_mfma_f32_16x16x32_bf16 v[96:99], v[142:145], v[222:225], v[96:99]
	v_mfma_f32_16x16x32_bf16 v[100:103], v[162:165], v[222:225], v[100:103]
	s_setprio 0
	s_setprio 1
	v_mfma_f32_16x16x32_bf16 v[24:27], v[166:169], v[184:187], v[24:27]
	v_mfma_f32_16x16x32_bf16 v[52:55], v[176:179], v[184:187], v[52:55]
	v_mfma_f32_16x16x32_bf16 v[44:47], v[166:169], v[192:195], v[44:47]
	v_mfma_f32_16x16x32_bf16 v[56:59], v[176:179], v[192:195], v[56:59]
	v_mfma_f32_16x16x32_bf16 v[72:75], v[166:169], v[200:203], v[72:75]
	v_mfma_f32_16x16x32_bf16 v[80:83], v[176:179], v[200:203], v[80:83]
	v_mfma_f32_16x16x32_bf16 v[104:107], v[166:169], v[218:221], v[104:107]
	v_mfma_f32_16x16x32_bf16 v[108:111], v[176:179], v[218:221], v[108:111]
	v_mfma_f32_16x16x32_bf16 v[24:27], v[170:173], v[188:191], v[24:27]
	v_mfma_f32_16x16x32_bf16 v[52:55], v[180:183], v[188:191], v[52:55]
	v_mfma_f32_16x16x32_bf16 v[44:47], v[170:173], v[196:199], v[44:47]
	v_mfma_f32_16x16x32_bf16 v[56:59], v[180:183], v[196:199], v[56:59]
	v_mfma_f32_16x16x32_bf16 v[72:75], v[170:173], v[204:207], v[72:75]
	v_mfma_f32_16x16x32_bf16 v[80:83], v[180:183], v[204:207], v[80:83]
	v_mfma_f32_16x16x32_bf16 v[104:107], v[170:173], v[222:225], v[104:107]
	v_mfma_f32_16x16x32_bf16 v[108:111], v[180:183], v[222:225], v[108:111]
	s_setprio 0
	s_barrier
	s_add_i32 s48, s49, s31
	v_lshl_add_u64 v[146:147], s[24:25], 0, v[148:149]
	s_mov_b32 m0, s48
	ds_read_b128 v[184:187], v136 offset:16384
	ds_read_b128 v[188:191], v136 offset:17408
	ds_read_b128 v[192:195], v136 offset:18432
	ds_read_b128 v[196:199], v136 offset:19456
	ds_read_b128 v[200:203], v136 offset:20480
	ds_read_b128 v[204:207], v136 offset:21504
	ds_read_b128 v[218:221], v136 offset:22528
	ds_read_b128 v[222:225], v136 offset:23552
	global_load_lds_dwordx4 v[146:147], off
	s_add_i32 m0, s48, 0x2000
	s_add_u32 s48, s24, 0x40000
	v_lshl_add_u64 v[154:155], s[24:25], 0, v[128:129]
	s_addc_u32 s49, s25, 0
	s_add_i32 s47, s47, s31
	global_load_lds_dwordx4 v[154:155], off
	v_lshl_add_u64 v[208:209], s[48:49], 0, v[148:149]
	s_mov_b32 m0, s47
	v_lshl_add_u64 v[212:213], s[26:27], 0, v[128:129]
	global_load_lds_dwordx4 v[208:209], off
	v_lshl_add_u64 v[208:209], s[48:49], 0, v[128:129]
	s_add_i32 m0, s47, 0x2000
	s_nop 0
	global_load_lds_dwordx4 v[208:209], off
	v_lshl_add_u64 v[208:209], s[26:27], 0, v[148:149]
	s_mov_b32 m0, s34
	s_nop 0
	global_load_lds_dwordx4 v[208:209], off
	s_mov_b32 m0, s35
	s_nop 0
	global_load_lds_dwordx4 v[212:213], off
	s_waitcnt vmcnt(8)
	s_waitcnt lgkmcnt(0)
	s_setprio 1
	s_barrier
	v_mfma_f32_16x16x32_bf16 v[124:127], v[138:141], v[184:187], v[124:127]
	v_mfma_f32_16x16x32_bf16 v[120:123], v[156:159], v[184:187], v[120:123]
	v_mfma_f32_16x16x32_bf16 v[92:95], v[138:141], v[192:195], v[92:95]
	v_mfma_f32_16x16x32_bf16 v[88:91], v[156:159], v[192:195], v[88:91]
	v_mfma_f32_16x16x32_bf16 v[60:63], v[138:141], v[200:203], v[60:63]
	v_mfma_f32_16x16x32_bf16 v[48:51], v[156:159], v[200:203], v[48:51]
	v_mfma_f32_16x16x32_bf16 v[12:15], v[138:141], v[218:221], v[12:15]
	v_mfma_f32_16x16x32_bf16 v[8:11], v[156:159], v[218:221], v[8:11]
	v_mfma_f32_16x16x32_bf16 v[124:127], v[142:145], v[188:191], v[124:127]
	v_mfma_f32_16x16x32_bf16 v[120:123], v[162:165], v[188:191], v[120:123]
	v_mfma_f32_16x16x32_bf16 v[92:95], v[142:145], v[196:199], v[92:95]
	v_mfma_f32_16x16x32_bf16 v[88:91], v[162:165], v[196:199], v[88:91]
	v_mfma_f32_16x16x32_bf16 v[60:63], v[142:145], v[204:207], v[60:63]
	v_mfma_f32_16x16x32_bf16 v[48:51], v[162:165], v[204:207], v[48:51]
	v_mfma_f32_16x16x32_bf16 v[12:15], v[142:145], v[222:225], v[12:15]
	v_mfma_f32_16x16x32_bf16 v[8:11], v[162:165], v[222:225], v[8:11]
	s_setprio 0
	s_setprio 1
	v_mfma_f32_16x16x32_bf16 v[116:119], v[166:169], v[184:187], v[116:119]
	v_mfma_f32_16x16x32_bf16 v[112:115], v[176:179], v[184:187], v[112:115]
	v_mfma_f32_16x16x32_bf16 v[84:87], v[166:169], v[192:195], v[84:87]
	v_mfma_f32_16x16x32_bf16 v[76:79], v[176:179], v[192:195], v[76:79]
	v_mfma_f32_16x16x32_bf16 v[32:35], v[166:169], v[200:203], v[32:35]
	v_mfma_f32_16x16x32_bf16 v[28:31], v[176:179], v[200:203], v[28:31]
	v_mfma_f32_16x16x32_bf16 v[4:7], v[166:169], v[218:221], v[4:7]
	v_mfma_f32_16x16x32_bf16 v[0:3], v[176:179], v[218:221], v[0:3]
	v_mfma_f32_16x16x32_bf16 v[116:119], v[170:173], v[188:191], v[116:119]
	v_mfma_f32_16x16x32_bf16 v[112:115], v[180:183], v[188:191], v[112:115]
	v_mfma_f32_16x16x32_bf16 v[84:87], v[170:173], v[196:199], v[84:87]
	v_mfma_f32_16x16x32_bf16 v[76:79], v[180:183], v[196:199], v[76:79]
	v_mfma_f32_16x16x32_bf16 v[32:35], v[170:173], v[204:207], v[32:35]
	v_mfma_f32_16x16x32_bf16 v[28:31], v[180:183], v[204:207], v[28:31]
	v_mfma_f32_16x16x32_bf16 v[4:7], v[170:173], v[222:225], v[4:7]
	v_mfma_f32_16x16x32_bf16 v[0:3], v[180:183], v[222:225], v[0:3]
	s_setprio 0
	s_barrier
	s_add_i32 s47, 0, 0x18000
	v_add_u32_e32 v137, s47, v135
	s_add_i32 s48, 0, 0x1c000
	ds_read_b128 v[138:141], v137
	ds_read_b128 v[142:145], v137 offset:1024
	ds_read_b128 v[156:159], v137 offset:2048
	ds_read_b128 v[162:165], v137 offset:3072
	v_add_u32_e32 v137, s48, v135
	ds_read_b128 v[166:169], v137
	ds_read_b128 v[170:173], v137 offset:1024
	ds_read_b128 v[176:179], v137 offset:2048
	ds_read_b128 v[180:183], v137 offset:3072
	s_add_u32 s26, s26, 0x40000
	s_addc_u32 s27, s27, 0
	s_mov_b32 m0, s36
	v_lshl_add_u64 v[226:227], s[26:27], 0, v[148:149]
	ds_read_b128 v[184:187], v136 offset:32768
	ds_read_b128 v[188:191], v136 offset:33792
	ds_read_b128 v[192:195], v136 offset:34816
	ds_read_b128 v[196:199], v136 offset:35840
	ds_read_b128 v[200:203], v136 offset:36864
	ds_read_b128 v[204:207], v136 offset:37888
	ds_read_b128 v[218:221], v136 offset:38912
	ds_read_b128 v[222:225], v136 offset:39936
	global_load_lds_dwordx4 v[226:227], off
	v_lshl_add_u64 v[226:227], s[26:27], 0, v[128:129]
	s_mov_b32 m0, s37
	s_nop 0
	global_load_lds_dwordx4 v[226:227], off
	s_waitcnt vmcnt(8)
	s_waitcnt lgkmcnt(0)
	s_setprio 1
	s_barrier
	v_mfma_f32_16x16x32_bf16 v[16:19], v[138:141], v[184:187], v[16:19]
	v_mfma_f32_16x16x32_bf16 v[20:23], v[156:159], v[184:187], v[20:23]
	v_mfma_f32_16x16x32_bf16 v[36:39], v[138:141], v[192:195], v[36:39]
	v_mfma_f32_16x16x32_bf16 v[40:43], v[156:159], v[192:195], v[40:43]
	v_mfma_f32_16x16x32_bf16 v[64:67], v[138:141], v[200:203], v[64:67]
	v_mfma_f32_16x16x32_bf16 v[68:71], v[156:159], v[200:203], v[68:71]
	v_mfma_f32_16x16x32_bf16 v[96:99], v[138:141], v[218:221], v[96:99]
	v_mfma_f32_16x16x32_bf16 v[100:103], v[156:159], v[218:221], v[100:103]
	v_mfma_f32_16x16x32_bf16 v[16:19], v[142:145], v[188:191], v[16:19]
	v_mfma_f32_16x16x32_bf16 v[20:23], v[162:165], v[188:191], v[20:23]
	v_mfma_f32_16x16x32_bf16 v[36:39], v[142:145], v[196:199], v[36:39]
	v_mfma_f32_16x16x32_bf16 v[40:43], v[162:165], v[196:199], v[40:43]
	v_mfma_f32_16x16x32_bf16 v[64:67], v[142:145], v[204:207], v[64:67]
	v_mfma_f32_16x16x32_bf16 v[68:71], v[162:165], v[204:207], v[68:71]
	v_mfma_f32_16x16x32_bf16 v[96:99], v[142:145], v[222:225], v[96:99]
	v_mfma_f32_16x16x32_bf16 v[100:103], v[162:165], v[222:225], v[100:103]
	s_setprio 0
	s_setprio 1
	v_mfma_f32_16x16x32_bf16 v[24:27], v[166:169], v[184:187], v[24:27]
	v_mfma_f32_16x16x32_bf16 v[52:55], v[176:179], v[184:187], v[52:55]
	v_mfma_f32_16x16x32_bf16 v[44:47], v[166:169], v[192:195], v[44:47]
	v_mfma_f32_16x16x32_bf16 v[56:59], v[176:179], v[192:195], v[56:59]
	v_mfma_f32_16x16x32_bf16 v[72:75], v[166:169], v[200:203], v[72:75]
	v_mfma_f32_16x16x32_bf16 v[80:83], v[176:179], v[200:203], v[80:83]
	v_mfma_f32_16x16x32_bf16 v[104:107], v[166:169], v[218:221], v[104:107]
	v_mfma_f32_16x16x32_bf16 v[108:111], v[176:179], v[218:221], v[108:111]
	v_mfma_f32_16x16x32_bf16 v[24:27], v[170:173], v[188:191], v[24:27]
	v_mfma_f32_16x16x32_bf16 v[52:55], v[180:183], v[188:191], v[52:55]
	v_mfma_f32_16x16x32_bf16 v[44:47], v[170:173], v[196:199], v[44:47]
	v_mfma_f32_16x16x32_bf16 v[56:59], v[180:183], v[196:199], v[56:59]
	v_mfma_f32_16x16x32_bf16 v[72:75], v[170:173], v[204:207], v[72:75]
	v_mfma_f32_16x16x32_bf16 v[80:83], v[180:183], v[204:207], v[80:83]
	v_mfma_f32_16x16x32_bf16 v[104:107], v[170:173], v[222:225], v[104:107]
	v_mfma_f32_16x16x32_bf16 v[108:111], v[180:183], v[222:225], v[108:111]
	s_setprio 0
	s_barrier
	s_add_i32 s26, s47, s31
	v_lshl_add_u64 v[146:147], v[146:147], 0, s[0:1]
	s_mov_b32 m0, s26
	ds_read_b128 v[184:187], v136 offset:49152
	ds_read_b128 v[188:191], v136 offset:50176
	ds_read_b128 v[192:195], v136 offset:51200
	ds_read_b128 v[196:199], v136 offset:52224
	ds_read_b128 v[200:203], v136 offset:53248
	ds_read_b128 v[204:207], v136 offset:54272
	ds_read_b128 v[218:221], v136 offset:55296
	ds_read_b128 v[222:225], v136 offset:56320
	global_load_lds_dwordx4 v[146:147], off
	s_add_i32 m0, s26, 0x2000
	s_add_u32 s24, s24, 0x40080
	v_lshl_add_u64 v[146:147], v[154:155], 0, s[0:1]
	s_addc_u32 s25, s25, 0
	s_add_i32 s26, s48, s31
	global_load_lds_dwordx4 v[146:147], off
	v_lshl_add_u64 v[146:147], s[24:25], 0, v[148:149]
	s_mov_b32 m0, s26
	s_nop 0
	global_load_lds_dwordx4 v[146:147], off
	v_lshl_add_u64 v[146:147], s[24:25], 0, v[128:129]
	s_add_i32 m0, s26, 0x2000
	s_nop 0
	global_load_lds_dwordx4 v[146:147], off
	v_lshl_add_u64 v[146:147], v[208:209], 0, s[0:1]
	s_mov_b32 m0, s38
	s_nop 0
	global_load_lds_dwordx4 v[146:147], off
	v_lshl_add_u64 v[146:147], v[212:213], 0, s[0:1]
	s_mov_b32 m0, s39
	s_nop 0
	global_load_lds_dwordx4 v[146:147], off
	s_waitcnt vmcnt(8)
	s_waitcnt lgkmcnt(0)
	s_setprio 1
	s_barrier
	v_mfma_f32_16x16x32_bf16 v[124:127], v[138:141], v[184:187], v[124:127]
	v_mfma_f32_16x16x32_bf16 v[120:123], v[156:159], v[184:187], v[120:123]
	v_mfma_f32_16x16x32_bf16 v[92:95], v[138:141], v[192:195], v[92:95]
	v_mfma_f32_16x16x32_bf16 v[88:91], v[156:159], v[192:195], v[88:91]
	v_mfma_f32_16x16x32_bf16 v[60:63], v[138:141], v[200:203], v[60:63]
	v_mfma_f32_16x16x32_bf16 v[48:51], v[156:159], v[200:203], v[48:51]
	v_mfma_f32_16x16x32_bf16 v[12:15], v[138:141], v[218:221], v[12:15]
	v_mfma_f32_16x16x32_bf16 v[8:11], v[156:159], v[218:221], v[8:11]
	v_mfma_f32_16x16x32_bf16 v[124:127], v[142:145], v[188:191], v[124:127]
	v_mfma_f32_16x16x32_bf16 v[120:123], v[162:165], v[188:191], v[120:123]
	v_mfma_f32_16x16x32_bf16 v[92:95], v[142:145], v[196:199], v[92:95]
	v_mfma_f32_16x16x32_bf16 v[88:91], v[162:165], v[196:199], v[88:91]
	v_mfma_f32_16x16x32_bf16 v[60:63], v[142:145], v[204:207], v[60:63]
	v_mfma_f32_16x16x32_bf16 v[48:51], v[162:165], v[204:207], v[48:51]
	v_mfma_f32_16x16x32_bf16 v[12:15], v[142:145], v[222:225], v[12:15]
	v_mfma_f32_16x16x32_bf16 v[8:11], v[162:165], v[222:225], v[8:11]
	s_setprio 0
	s_setprio 1
	v_mfma_f32_16x16x32_bf16 v[116:119], v[166:169], v[184:187], v[116:119]
	v_mfma_f32_16x16x32_bf16 v[112:115], v[176:179], v[184:187], v[112:115]
	v_mfma_f32_16x16x32_bf16 v[84:87], v[166:169], v[192:195], v[84:87]
	v_mfma_f32_16x16x32_bf16 v[76:79], v[176:179], v[192:195], v[76:79]
	v_mfma_f32_16x16x32_bf16 v[32:35], v[166:169], v[200:203], v[32:35]
	v_mfma_f32_16x16x32_bf16 v[28:31], v[176:179], v[200:203], v[28:31]
	v_mfma_f32_16x16x32_bf16 v[4:7], v[166:169], v[218:221], v[4:7]
	v_mfma_f32_16x16x32_bf16 v[0:3], v[176:179], v[218:221], v[0:3]
	v_mfma_f32_16x16x32_bf16 v[116:119], v[170:173], v[188:191], v[116:119]
	v_mfma_f32_16x16x32_bf16 v[112:115], v[180:183], v[188:191], v[112:115]
	v_mfma_f32_16x16x32_bf16 v[84:87], v[170:173], v[196:199], v[84:87]
	v_mfma_f32_16x16x32_bf16 v[76:79], v[180:183], v[196:199], v[76:79]
	v_mfma_f32_16x16x32_bf16 v[32:35], v[170:173], v[204:207], v[32:35]
	v_mfma_f32_16x16x32_bf16 v[28:31], v[180:183], v[204:207], v[28:31]
	v_mfma_f32_16x16x32_bf16 v[4:7], v[170:173], v[222:225], v[4:7]
	v_mfma_f32_16x16x32_bf16 v[0:3], v[180:183], v[222:225], v[0:3]
	s_setprio 0
	s_barrier
	s_add_i32 s46, s46, 2
	s_add_u32 s22, s22, 0x100
	s_addc_u32 s23, s23, 0
	s_cmp_lt_u32 s46, 14
	s_cbranch_scc1 .LBB0_985
	s_waitcnt vmcnt(0)
	s_cmpk_gt_u32 s28, 0xff
	s_cbranch_scc1 .LBB0_988
	s_barrier

.LBB0_1099:
	s_lshl_b32 s64, s89, 7
	s_add_u32 s65, s22, s64
	s_addc_u32 s90, s23, 0
	s_add_u32 s62, s65, 0x100
	s_addc_u32 s63, s90, 0
	s_and_b64 s[58:59], s[60:61], exec
	s_cselect_b32 s63, s35, s63
	s_cselect_b32 s62, s84, s62
	s_add_u32 s58, s24, s64
	s_addc_u32 s59, s25, 0
	s_add_u32 s91, s58, 0x100
	s_addc_u32 s92, s59, 0
	s_and_b64 s[58:59], s[60:61], exec
	s_cselect_b32 s59, s29, s92
	s_cselect_b32 s58, s85, s91
	s_add_u32 s64, s26, s64
	s_addc_u32 s91, s27, 0
	s_add_u32 s64, s64, 0x100
	s_addc_u32 s91, s91, 0
	s_and_b64 s[60:61], s[60:61], exec
	s_cselect_b32 s91, s31, s91
	s_cselect_b32 s64, s88, s64
	s_add_i32 s92, 0, 0x10000
	v_add_u32_e32 v154, s92, v19
	s_add_i32 s93, 0, 0x14000
	ds_read_b128 v[158:161], v154
	ds_read_b128 v[162:165], v154 offset:1024
	ds_read_b128 v[166:169], v154 offset:2048
	ds_read_b128 v[170:173], v154 offset:3072
	v_add_u32_e32 v154, s93, v19
	ds_read_b128 v[174:177], v154
	ds_read_b128 v[178:181], v154 offset:1024
	ds_read_b128 v[182:185], v154 offset:2048
	ds_read_b128 v[186:189], v154 offset:3072
	s_add_i32 s94, 0, 0x20000
	s_add_u32 s60, s65, 0x40080
	s_addc_u32 s61, s90, 0
	v_add_u32_e32 v154, 0, v18
	v_add_u32_e32 v155, s94, v156
	v_lshl_add_u64 v[212:213], s[60:61], 0, v[148:149]
	s_add_i32 m0, s71, 0xc000
	ds_read_b128 v[190:193], v154
	ds_read_b128 v[194:197], v154 offset:1024
	ds_read_b128 v[198:201], v154 offset:2048
	ds_read_b128 v[202:205], v154 offset:3072
	ds_read_b128 v[206:209], v154 offset:4096
	ds_read_b128 v[218:221], v154 offset:5120
	ds_read_b128 v[222:225], v154 offset:6144
	ds_read_b128 v[226:229], v154 offset:7168
	ds_read_b128 v[230:233], v155
	ds_read_b128 v[234:237], v155 offset:1024
	global_load_lds_dwordx4 v[212:213], off
	v_lshl_add_u64 v[212:213], s[60:61], 0, v[16:17]
	s_add_i32 m0, s71, 0xe000
	s_nop 0
	global_load_lds_dwordx4 v[212:213], off
	s_waitcnt vmcnt(9)
	s_waitcnt lgkmcnt(0)
	s_setprio 1
	s_barrier
	v_mfma_f32_16x16x32_bf16 v[144:147], v[158:161], v[190:193], v[144:147]
	v_mfma_f32_16x16x32_bf16 v[140:143], v[166:169], v[190:193], v[140:143]
	v_mfma_f32_16x16x32_bf16 v[132:135], v[158:161], v[198:201], v[132:135]
	v_mfma_f32_16x16x32_bf16 v[128:131], v[166:169], v[198:201], v[128:131]
	v_mfma_f32_16x16x32_bf16 v[120:123], v[158:161], v[206:209], v[120:123]
	v_mfma_f32_16x16x32_bf16 v[112:115], v[166:169], v[206:209], v[112:115]
	v_mfma_f32_16x16x32_bf16 v[104:107], v[158:161], v[222:225], v[104:107]
	v_mfma_f32_16x16x32_bf16 v[96:99], v[166:169], v[222:225], v[96:99]
	v_mfma_f32_16x16x32_bf16 v[144:147], v[162:165], v[194:197], v[144:147]
	v_mfma_f32_16x16x32_bf16 v[140:143], v[170:173], v[194:197], v[140:143]
	v_mfma_f32_16x16x32_bf16 v[132:135], v[162:165], v[202:205], v[132:135]
	v_mfma_f32_16x16x32_bf16 v[128:131], v[170:173], v[202:205], v[128:131]
	v_mfma_f32_16x16x32_bf16 v[120:123], v[162:165], v[218:221], v[120:123]
	v_mfma_f32_16x16x32_bf16 v[112:115], v[170:173], v[218:221], v[112:115]
	v_mfma_f32_16x16x32_bf16 v[104:107], v[162:165], v[226:229], v[104:107]
	v_mfma_f32_16x16x32_bf16 v[96:99], v[170:173], v[226:229], v[96:99]
	s_setprio 0
	s_setprio 1
	v_mfma_f32_16x16x32_bf16 v[136:139], v[174:177], v[190:193], v[136:139]
	v_mfma_f32_16x16x32_bf16 v[124:127], v[182:185], v[190:193], v[124:127]
	v_mfma_f32_16x16x32_bf16 v[116:119], v[174:177], v[198:201], v[116:119]
	v_mfma_f32_16x16x32_bf16 v[108:111], v[182:185], v[198:201], v[108:111]
	v_mfma_f32_16x16x32_bf16 v[100:103], v[174:177], v[206:209], v[100:103]
	v_mfma_f32_16x16x32_bf16 v[92:95], v[182:185], v[206:209], v[92:95]
	v_mfma_f32_16x16x32_bf16 v[88:91], v[174:177], v[222:225], v[88:91]
	v_mfma_f32_16x16x32_bf16 v[84:87], v[182:185], v[222:225], v[84:87]
	v_mfma_f32_16x16x32_bf16 v[136:139], v[178:181], v[194:197], v[136:139]
	v_mfma_f32_16x16x32_bf16 v[124:127], v[186:189], v[194:197], v[124:127]
	v_mfma_f32_16x16x32_bf16 v[116:119], v[178:181], v[202:205], v[116:119]
	v_mfma_f32_16x16x32_bf16 v[108:111], v[186:189], v[202:205], v[108:111]
	v_mfma_f32_16x16x32_bf16 v[100:103], v[178:181], v[218:221], v[100:103]
	v_mfma_f32_16x16x32_bf16 v[92:95], v[186:189], v[218:221], v[92:95]
	v_mfma_f32_16x16x32_bf16 v[88:91], v[178:181], v[226:229], v[88:91]
	v_mfma_f32_16x16x32_bf16 v[84:87], v[186:189], v[226:229], v[84:87]
	s_setprio 0
	v_mfma_f32_16x16x32_bf16 v[12:15], v[158:161], v[230:233], v[12:15]
	s_barrier
	v_mfma_f32_16x16x32_bf16 v[4:7], v[174:177], v[230:233], v[4:7]
	v_mfma_f32_16x16x32_bf16 v[8:11], v[166:169], v[230:233], v[8:11]
	v_mfma_f32_16x16x32_bf16 v[0:3], v[182:185], v[230:233], v[0:3]
	v_mfma_f32_16x16x32_bf16 v[12:15], v[162:165], v[234:237], v[12:15]
	v_mfma_f32_16x16x32_bf16 v[4:7], v[178:181], v[234:237], v[4:7]
	v_mfma_f32_16x16x32_bf16 v[8:11], v[170:173], v[234:237], v[8:11]
	v_mfma_f32_16x16x32_bf16 v[0:3], v[186:189], v[234:237], v[0:3]
	s_add_i32 s60, s92, s77
	v_lshl_add_u64 v[212:213], s[58:59], 0, v[148:149]
	s_mov_b32 m0, s60
	ds_read_b128 v[190:193], v154 offset:16384
	ds_read_b128 v[194:197], v154 offset:17408
	ds_read_b128 v[198:201], v154 offset:18432
	ds_read_b128 v[202:205], v154 offset:19456
	ds_read_b128 v[206:209], v154 offset:20480
	ds_read_b128 v[218:221], v154 offset:21504
	ds_read_b128 v[222:225], v154 offset:22528
	ds_read_b128 v[226:229], v154 offset:23552
	global_load_lds_dwordx4 v[212:213], off
	s_add_i32 m0, s60, 0x2000
	s_add_u32 s60, s58, 0x40000
	v_lshl_add_u64 v[238:239], s[58:59], 0, v[16:17]
	s_addc_u32 s61, s59, 0
	s_add_i32 s65, s93, s77
	global_load_lds_dwordx4 v[238:239], off
	v_lshl_add_u64 v[230:231], s[60:61], 0, v[148:149]
	s_mov_b32 m0, s65
	v_lshl_add_u64 v[240:241], s[62:63], 0, v[148:149]
	global_load_lds_dwordx4 v[230:231], off
	v_lshl_add_u64 v[230:231], s[60:61], 0, v[16:17]
	s_add_i32 m0, s65, 0x2000
	s_add_u32 s60, s64, s76
	global_load_lds_dwordx4 v[230:231], off
	s_mov_b32 m0, s71
	v_lshl_add_u64 v[242:243], s[62:63], 0, v[16:17]
	global_load_lds_dwordx4 v[240:241], off
	s_mov_b32 m0, s78
	s_addc_u32 s61, s91, s75
	global_load_lds_dwordx4 v[242:243], off
	v_lshl_add_u64 v[244:245], s[60:61], 0, v[148:149]
	s_add_i32 m0, s94, s79
	s_nop 0
	global_load_lds_dwordx4 v[244:245], off
	s_waitcnt vmcnt(9)
	s_waitcnt lgkmcnt(0)
	s_setprio 1
	s_barrier
	v_mfma_f32_16x16x32_bf16 v[80:83], v[158:161], v[190:193], v[80:83]
	v_mfma_f32_16x16x32_bf16 v[76:79], v[166:169], v[190:193], v[76:79]
	v_mfma_f32_16x16x32_bf16 v[72:75], v[158:161], v[198:201], v[72:75]
	v_mfma_f32_16x16x32_bf16 v[64:67], v[166:169], v[198:201], v[64:67]
	v_mfma_f32_16x16x32_bf16 v[56:59], v[158:161], v[206:209], v[56:59]
	v_mfma_f32_16x16x32_bf16 v[48:51], v[166:169], v[206:209], v[48:51]
	v_mfma_f32_16x16x32_bf16 v[40:43], v[158:161], v[222:225], v[40:43]
	v_mfma_f32_16x16x32_bf16 v[32:35], v[166:169], v[222:225], v[32:35]
	v_mfma_f32_16x16x32_bf16 v[80:83], v[162:165], v[194:197], v[80:83]
	v_mfma_f32_16x16x32_bf16 v[76:79], v[170:173], v[194:197], v[76:79]
	v_mfma_f32_16x16x32_bf16 v[72:75], v[162:165], v[202:205], v[72:75]
	v_mfma_f32_16x16x32_bf16 v[64:67], v[170:173], v[202:205], v[64:67]
	v_mfma_f32_16x16x32_bf16 v[56:59], v[162:165], v[218:221], v[56:59]
	v_mfma_f32_16x16x32_bf16 v[48:51], v[170:173], v[218:221], v[48:51]
	v_mfma_f32_16x16x32_bf16 v[40:43], v[162:165], v[226:229], v[40:43]
	v_mfma_f32_16x16x32_bf16 v[32:35], v[170:173], v[226:229], v[32:35]
	s_setprio 0
	s_setprio 1
	v_mfma_f32_16x16x32_bf16 v[68:71], v[174:177], v[190:193], v[68:71]
	v_mfma_f32_16x16x32_bf16 v[60:63], v[182:185], v[190:193], v[60:63]
	v_mfma_f32_16x16x32_bf16 v[52:55], v[174:177], v[198:201], v[52:55]
	v_mfma_f32_16x16x32_bf16 v[44:47], v[182:185], v[198:201], v[44:47]
	v_mfma_f32_16x16x32_bf16 v[36:39], v[174:177], v[206:209], v[36:39]
	v_mfma_f32_16x16x32_bf16 v[28:31], v[182:185], v[206:209], v[28:31]
	v_mfma_f32_16x16x32_bf16 v[24:27], v[174:177], v[222:225], v[24:27]
	v_mfma_f32_16x16x32_bf16 v[20:23], v[182:185], v[222:225], v[20:23]
	v_mfma_f32_16x16x32_bf16 v[68:71], v[178:181], v[194:197], v[68:71]
	v_mfma_f32_16x16x32_bf16 v[60:63], v[186:189], v[194:197], v[60:63]
	v_mfma_f32_16x16x32_bf16 v[52:55], v[178:181], v[202:205], v[52:55]
	v_mfma_f32_16x16x32_bf16 v[44:47], v[186:189], v[202:205], v[44:47]
	v_mfma_f32_16x16x32_bf16 v[36:39], v[178:181], v[218:221], v[36:39]
	v_mfma_f32_16x16x32_bf16 v[28:31], v[186:189], v[218:221], v[28:31]
	v_mfma_f32_16x16x32_bf16 v[24:27], v[178:181], v[226:229], v[24:27]
	v_mfma_f32_16x16x32_bf16 v[20:23], v[186:189], v[226:229], v[20:23]
	s_setprio 0
	s_barrier
	s_add_i32 s64, 0, 0x18000
	v_add_u32_e32 v155, s64, v19
	s_add_i32 s65, 0, 0x1c000
	ds_read_b128 v[158:161], v155
	ds_read_b128 v[162:165], v155 offset:1024
	ds_read_b128 v[166:169], v155 offset:2048
	ds_read_b128 v[170:173], v155 offset:3072
	v_add_u32_e32 v155, s65, v19
	ds_read_b128 v[174:177], v155
	ds_read_b128 v[178:181], v155 offset:1024
	ds_read_b128 v[182:185], v155 offset:2048
	ds_read_b128 v[186:189], v155 offset:3072
	s_add_i32 s90, 0, 0x21000
	s_add_u32 s60, s62, 0x40000
	s_addc_u32 s61, s63, 0
	s_mov_b32 m0, s80
	v_add_u32_e32 v155, s90, v156
	v_lshl_add_u64 v[246:247], s[60:61], 0, v[148:149]
	ds_read_b128 v[190:193], v154 offset:32768
	ds_read_b128 v[194:197], v154 offset:33792
	ds_read_b128 v[198:201], v154 offset:34816
	ds_read_b128 v[202:205], v154 offset:35840
	ds_read_b128 v[206:209], v154 offset:36864
	ds_read_b128 v[218:221], v154 offset:37888
	ds_read_b128 v[222:225], v154 offset:38912
	ds_read_b128 v[226:229], v154 offset:39936
	ds_read_b128 v[230:233], v155
	ds_read_b128 v[234:237], v155 offset:1024
	global_load_lds_dwordx4 v[246:247], off
	v_lshl_add_u64 v[246:247], s[60:61], 0, v[16:17]
	s_mov_b32 m0, s81
	s_nop 0
	global_load_lds_dwordx4 v[246:247], off
	s_waitcnt vmcnt(9)
	s_waitcnt lgkmcnt(0)
	s_setprio 1
	s_barrier
	v_mfma_f32_16x16x32_bf16 v[144:147], v[158:161], v[190:193], v[144:147]
	v_mfma_f32_16x16x32_bf16 v[140:143], v[166:169], v[190:193], v[140:143]
	v_mfma_f32_16x16x32_bf16 v[132:135], v[158:161], v[198:201], v[132:135]
	v_mfma_f32_16x16x32_bf16 v[128:131], v[166:169], v[198:201], v[128:131]
	v_mfma_f32_16x16x32_bf16 v[120:123], v[158:161], v[206:209], v[120:123]
	v_mfma_f32_16x16x32_bf16 v[112:115], v[166:169], v[206:209], v[112:115]
	v_mfma_f32_16x16x32_bf16 v[104:107], v[158:161], v[222:225], v[104:107]
	v_mfma_f32_16x16x32_bf16 v[96:99], v[166:169], v[222:225], v[96:99]
	v_mfma_f32_16x16x32_bf16 v[144:147], v[162:165], v[194:197], v[144:147]
	v_mfma_f32_16x16x32_bf16 v[140:143], v[170:173], v[194:197], v[140:143]
	v_mfma_f32_16x16x32_bf16 v[132:135], v[162:165], v[202:205], v[132:135]
	v_mfma_f32_16x16x32_bf16 v[128:131], v[170:173], v[202:205], v[128:131]
	v_mfma_f32_16x16x32_bf16 v[120:123], v[162:165], v[218:221], v[120:123]
	v_mfma_f32_16x16x32_bf16 v[112:115], v[170:173], v[218:221], v[112:115]
	v_mfma_f32_16x16x32_bf16 v[104:107], v[162:165], v[226:229], v[104:107]
	v_mfma_f32_16x16x32_bf16 v[96:99], v[170:173], v[226:229], v[96:99]
	s_setprio 0
	s_setprio 1
	v_mfma_f32_16x16x32_bf16 v[136:139], v[174:177], v[190:193], v[136:139]
	v_mfma_f32_16x16x32_bf16 v[124:127], v[182:185], v[190:193], v[124:127]
	v_mfma_f32_16x16x32_bf16 v[116:119], v[174:177], v[198:201], v[116:119]
	v_mfma_f32_16x16x32_bf16 v[108:111], v[182:185], v[198:201], v[108:111]
	v_mfma_f32_16x16x32_bf16 v[100:103], v[174:177], v[206:209], v[100:103]
	v_mfma_f32_16x16x32_bf16 v[92:95], v[182:185], v[206:209], v[92:95]
	v_mfma_f32_16x16x32_bf16 v[88:91], v[174:177], v[222:225], v[88:91]
	v_mfma_f32_16x16x32_bf16 v[84:87], v[182:185], v[222:225], v[84:87]
	v_mfma_f32_16x16x32_bf16 v[136:139], v[178:181], v[194:197], v[136:139]
	v_mfma_f32_16x16x32_bf16 v[124:127], v[186:189], v[194:197], v[124:127]
	v_mfma_f32_16x16x32_bf16 v[116:119], v[178:181], v[202:205], v[116:119]
	v_mfma_f32_16x16x32_bf16 v[108:111], v[186:189], v[202:205], v[108:111]
	v_mfma_f32_16x16x32_bf16 v[100:103], v[178:181], v[218:221], v[100:103]
	v_mfma_f32_16x16x32_bf16 v[92:95], v[186:189], v[218:221], v[92:95]
	v_mfma_f32_16x16x32_bf16 v[88:91], v[178:181], v[226:229], v[88:91]
	v_mfma_f32_16x16x32_bf16 v[84:87], v[186:189], v[226:229], v[84:87]
	s_setprio 0
	v_mfma_f32_16x16x32_bf16 v[12:15], v[158:161], v[230:233], v[12:15]
	s_barrier
	v_mfma_f32_16x16x32_bf16 v[4:7], v[174:177], v[230:233], v[4:7]
	v_mfma_f32_16x16x32_bf16 v[8:11], v[166:169], v[230:233], v[8:11]
	v_mfma_f32_16x16x32_bf16 v[0:3], v[182:185], v[230:233], v[0:3]
	v_mfma_f32_16x16x32_bf16 v[12:15], v[162:165], v[234:237], v[12:15]
	v_mfma_f32_16x16x32_bf16 v[4:7], v[178:181], v[234:237], v[4:7]
	v_mfma_f32_16x16x32_bf16 v[8:11], v[170:173], v[234:237], v[8:11]
	v_mfma_f32_16x16x32_bf16 v[0:3], v[186:189], v[234:237], v[0:3]
	s_add_i32 s60, s64, s77
	v_lshl_add_u64 v[212:213], v[212:213], 0, s[0:1]
	s_mov_b32 m0, s60
	ds_read_b128 v[190:193], v154 offset:49152
	ds_read_b128 v[194:197], v154 offset:50176
	ds_read_b128 v[198:201], v154 offset:51200
	ds_read_b128 v[202:205], v154 offset:52224
	ds_read_b128 v[206:209], v154 offset:53248
	ds_read_b128 v[218:221], v154 offset:54272
	ds_read_b128 v[222:225], v154 offset:55296
	ds_read_b128 v[226:229], v154 offset:56320
	global_load_lds_dwordx4 v[212:213], off
	s_add_i32 m0, s60, 0x2000
	s_add_u32 s58, s58, 0x40080
	v_lshl_add_u64 v[212:213], v[238:239], 0, s[0:1]
	s_addc_u32 s59, s59, 0
	s_add_i32 s60, s65, s77
	global_load_lds_dwordx4 v[212:213], off
	v_lshl_add_u64 v[212:213], s[58:59], 0, v[148:149]
	s_mov_b32 m0, s60
	s_nop 0
	global_load_lds_dwordx4 v[212:213], off
	v_lshl_add_u64 v[212:213], s[58:59], 0, v[16:17]
	s_add_i32 m0, s60, 0x2000
	s_nop 0
	global_load_lds_dwordx4 v[212:213], off
	v_lshl_add_u64 v[212:213], v[240:241], 0, s[0:1]
	s_mov_b32 m0, s5
	s_nop 0
	global_load_lds_dwordx4 v[212:213], off
	v_lshl_add_u64 v[212:213], v[242:243], 0, s[0:1]
	s_mov_b32 m0, s82
	s_nop 0
	global_load_lds_dwordx4 v[212:213], off
	v_lshl_add_u64 v[212:213], v[244:245], 0, s[0:1]
	s_add_i32 m0, s90, s79
	s_nop 0
	global_load_lds_dwordx4 v[212:213], off
	s_waitcnt vmcnt(9)
	s_waitcnt lgkmcnt(0)
	s_setprio 1
	s_barrier
	v_mfma_f32_16x16x32_bf16 v[80:83], v[158:161], v[190:193], v[80:83]
	v_mfma_f32_16x16x32_bf16 v[76:79], v[166:169], v[190:193], v[76:79]
	v_mfma_f32_16x16x32_bf16 v[72:75], v[158:161], v[198:201], v[72:75]
	v_mfma_f32_16x16x32_bf16 v[64:67], v[166:169], v[198:201], v[64:67]
	v_mfma_f32_16x16x32_bf16 v[56:59], v[158:161], v[206:209], v[56:59]
	v_mfma_f32_16x16x32_bf16 v[48:51], v[166:169], v[206:209], v[48:51]
	v_mfma_f32_16x16x32_bf16 v[40:43], v[158:161], v[222:225], v[40:43]
	v_mfma_f32_16x16x32_bf16 v[32:35], v[166:169], v[222:225], v[32:35]
	v_mfma_f32_16x16x32_bf16 v[80:83], v[162:165], v[194:197], v[80:83]
	v_mfma_f32_16x16x32_bf16 v[76:79], v[170:173], v[194:197], v[76:79]
	v_mfma_f32_16x16x32_bf16 v[72:75], v[162:165], v[202:205], v[72:75]
	v_mfma_f32_16x16x32_bf16 v[64:67], v[170:173], v[202:205], v[64:67]
	v_mfma_f32_16x16x32_bf16 v[56:59], v[162:165], v[218:221], v[56:59]
	v_mfma_f32_16x16x32_bf16 v[48:51], v[170:173], v[218:221], v[48:51]
	v_mfma_f32_16x16x32_bf16 v[40:43], v[162:165], v[226:229], v[40:43]
	v_mfma_f32_16x16x32_bf16 v[32:35], v[170:173], v[226:229], v[32:35]
	s_setprio 0
	s_setprio 1
	v_mfma_f32_16x16x32_bf16 v[68:71], v[174:177], v[190:193], v[68:71]
	v_mfma_f32_16x16x32_bf16 v[60:63], v[182:185], v[190:193], v[60:63]
	v_mfma_f32_16x16x32_bf16 v[52:55], v[174:177], v[198:201], v[52:55]
	v_mfma_f32_16x16x32_bf16 v[44:47], v[182:185], v[198:201], v[44:47]
	v_mfma_f32_16x16x32_bf16 v[36:39], v[174:177], v[206:209], v[36:39]
	v_mfma_f32_16x16x32_bf16 v[28:31], v[182:185], v[206:209], v[28:31]
	v_mfma_f32_16x16x32_bf16 v[24:27], v[174:177], v[222:225], v[24:27]
	v_mfma_f32_16x16x32_bf16 v[20:23], v[182:185], v[222:225], v[20:23]
	v_mfma_f32_16x16x32_bf16 v[68:71], v[178:181], v[194:197], v[68:71]
	v_mfma_f32_16x16x32_bf16 v[60:63], v[186:189], v[194:197], v[60:63]
	v_mfma_f32_16x16x32_bf16 v[52:55], v[178:181], v[202:205], v[52:55]
	v_mfma_f32_16x16x32_bf16 v[44:47], v[186:189], v[202:205], v[44:47]
	v_mfma_f32_16x16x32_bf16 v[36:39], v[178:181], v[218:221], v[36:39]
	v_mfma_f32_16x16x32_bf16 v[28:31], v[186:189], v[218:221], v[28:31]
	v_mfma_f32_16x16x32_bf16 v[24:27], v[178:181], v[226:229], v[24:27]
	v_mfma_f32_16x16x32_bf16 v[20:23], v[186:189], v[226:229], v[20:23]
	s_setprio 0
	s_barrier
	s_add_i32 s58, s89, 2
	s_cmp_gt_u32 s89, 13
	s_cbranch_scc1 .LBB0_1101
	s_mov_b32 s89, s58
	s_branch .LBB0_1085
